# GEMM loops: loop-back barrier rotated to the loop head; exit test, k advance and next trip's k-offset SALU moved in front of it (7.11)
# baseline (speedup 1.0000x reference)
.LBB0_122:
	v_readfirstlane_b32 s10, v100
	v_readfirstlane_b32 s11, v101
	v_readfirstlane_b32 s12, v104
	v_readfirstlane_b32 s13, v105
	v_readfirstlane_b32 s14, v106
	v_readfirstlane_b32 s15, v107
	v_readfirstlane_b32 s16, v108
	v_readfirstlane_b32 s17, v109
	v_readfirstlane_b32 s18, v102
	v_readfirstlane_b32 s19, v103
	v_readfirstlane_b32 s20, v110
	v_readfirstlane_b32 s21, v111
	v_readfirstlane_b32 s22, v112
	v_readfirstlane_b32 s23, v113
	v_subrev_u32_e32 v140, s10, v100
	v_subrev_u32_e32 v141, s18, v102
	s_nop 4
	s_add_i32 s7, s6, 64
	s_min_u32 s8, s7, 0xae0
	s_lshl_b32 s78, s8, 1
	ds_read_b128 v[52:55], v116 offset:0
	ds_read_b128 v[48:51], v116 offset:0x800
	ds_read_b128 v[44:47], v116 offset:0x1000
	ds_read_b128 v[96:99], v114 offset:0
	ds_read_b128 v[92:95], v114 offset:0x800
	ds_read_b128 v[88:91], v114 offset:0x1000
	v_add_u32_e32 v142, s78, v140
	v_add_u32_e32 v143, s78, v141
	global_load_dwordx4 v[64:67], v142, s[10:11]
	ds_read_b128 v[56:59], v114 offset:0x1800
	global_load_dwordx4 v[60:63], v142, s[12:13]
	global_load_dwordx4 v[72:75], v142, s[14:15]
	global_load_dwordx4 v[68:71], v142, s[16:17]
	global_load_dwordx4 v[84:87], v143, s[18:19]
	s_waitcnt lgkmcnt(3)
	v_mfma_f32_32x32x16_bf16 a[48:63], v[96:99], v[52:55], 0
	ds_read_b128 v[36:39], v117 offset:0
	v_mfma_f32_32x32x16_bf16 a[64:79], v[96:99], v[48:51], 0
	global_load_dwordx4 v[76:79], v143, s[20:21]
	v_mfma_f32_32x32x16_bf16 a[80:95], v[96:99], v[44:47], 0
	ds_read_b128 v[40:43], v117 offset:0x800
	s_waitcnt lgkmcnt(4)
	v_mfma_f32_32x32x16_bf16 a[96:111], v[92:95], v[52:55], 0
	global_load_dwordx4 v[80:83], v143, s[22:23]
	v_mfma_f32_32x32x16_bf16 a[112:127], v[92:95], v[48:51], 0
	ds_read_b128 v[120:123], v117 offset:0x1000
	v_mfma_f32_32x32x16_bf16 a[128:143], v[92:95], v[44:47], 0
	ds_read_b128 v[124:127], v115 offset:0
	s_waitcnt lgkmcnt(5)
	v_mfma_f32_32x32x16_bf16 a[144:159], v[88:91], v[52:55], 0
	ds_read_b128 v[128:131], v115 offset:0x800
	s_min_u32 s6, s6, 0xa80
	s_lshl_b32 s78, s6, 1
	v_mfma_f32_32x32x16_bf16 a[160:175], v[88:91], v[48:51], 0
	ds_read_b128 v[132:135], v115 offset:0x1000
	s_add_i32 s8, s78, 0xc0
	s_mov_b32 s9, s79
	v_mfma_f32_32x32x16_bf16 a[176:191], v[88:91], v[44:47], 0
	ds_read_b128 v[136:139], v115 offset:0x1800
	s_add_i32 s5, s5, 2
	s_cmpk_lt_u32 s5, 0x56
	s_waitcnt lgkmcnt(7)
	v_mfma_f32_32x32x16_bf16 a[32:47], v[56:59], v[52:55], 0
	s_waitcnt vmcnt(13)
	ds_write_b128 v118, v[4:7] offset:0x8000
	v_mfma_f32_32x32x16_bf16 a[16:31], v[56:59], v[48:51], 0
	s_waitcnt vmcnt(12)
	ds_write_b128 v118, v[8:11] offset:0x9000
	v_mfma_f32_32x32x16_bf16 a[0:15], v[56:59], v[44:47], 0
	s_waitcnt vmcnt(11)
	ds_write_b128 v118, v[12:15] offset:0xa000
	s_waitcnt lgkmcnt(6)
	v_mfma_f32_32x32x16_bf16 a[48:63], v[124:127], v[36:39], a[48:63]
	s_waitcnt vmcnt(10)
	ds_write_b128 v118, v[16:19] offset:0xb000
	v_mfma_f32_32x32x16_bf16 a[64:79], v[124:127], v[40:43], a[64:79]
	s_waitcnt vmcnt(9)
	ds_write_b128 v118, v[20:23] offset:0xc000
	v_mfma_f32_32x32x16_bf16 a[80:95], v[124:127], v[120:123], a[80:95]
	s_waitcnt vmcnt(8)
	ds_write_b128 v118, v[24:27] offset:0xd000
	s_waitcnt lgkmcnt(8)
	v_mfma_f32_32x32x16_bf16 a[96:111], v[128:131], v[36:39], a[96:111]
	s_waitcnt vmcnt(7)
	ds_write_b128 v118, v[28:31] offset:0xe000
	v_mfma_f32_32x32x16_bf16 a[112:127], v[128:131], v[40:43], a[112:127]
	v_mfma_f32_32x32x16_bf16 a[128:143], v[128:131], v[120:123], a[128:143]
	s_waitcnt lgkmcnt(0)
	s_barrier
	ds_read_b128 v[44:47], v116 offset:0x8000
	ds_read_b128 v[48:51], v116 offset:0x8800
	ds_read_b128 v[52:55], v116 offset:0x9000
	ds_read_b128 v[56:59], v114 offset:0x8000
	v_mfma_f32_32x32x16_bf16 a[144:159], v[132:135], v[36:39], a[144:159]
	ds_read_b128 v[88:91], v114 offset:0x8800
	v_mfma_f32_32x32x16_bf16 a[160:175], v[132:135], v[40:43], a[160:175]
	ds_read_b128 v[92:95], v114 offset:0x9000
	v_add_u32_e32 v142, s8, v140
	v_add_u32_e32 v143, s8, v141
	global_load_dwordx4 v[4:7], v142, s[10:11]
	v_mfma_f32_32x32x16_bf16 a[176:191], v[132:135], v[120:123], a[176:191]
	ds_read_b128 v[96:99], v114 offset:0x9800
	global_load_dwordx4 v[8:11], v142, s[12:13]
	v_mfma_f32_32x32x16_bf16 a[32:47], v[136:139], v[36:39], a[32:47]
	global_load_dwordx4 v[12:15], v142, s[14:15]
	v_mfma_f32_32x32x16_bf16 a[16:31], v[136:139], v[40:43], a[16:31]
	global_load_dwordx4 v[16:19], v142, s[16:17]
	v_mfma_f32_32x32x16_bf16 a[0:15], v[136:139], v[120:123], a[0:15]
	global_load_dwordx4 v[20:23], v143, s[18:19]
	s_waitcnt lgkmcnt(3)
	v_mfma_f32_32x32x16_bf16 a[48:63], v[56:59], v[44:47], a[48:63]
	ds_read_b128 v[40:43], v117 offset:0x8000
	v_mfma_f32_32x32x16_bf16 a[64:79], v[56:59], v[48:51], a[64:79]
	global_load_dwordx4 v[24:27], v143, s[20:21]
	v_mfma_f32_32x32x16_bf16 a[80:95], v[56:59], v[52:55], a[80:95]
	ds_read_b128 v[36:39], v117 offset:0x8800
	s_waitcnt lgkmcnt(4)
	v_mfma_f32_32x32x16_bf16 a[96:111], v[88:91], v[44:47], a[96:111]
	global_load_dwordx4 v[28:31], v143, s[22:23]
	v_mfma_f32_32x32x16_bf16 a[112:127], v[88:91], v[48:51], a[112:127]
	ds_read_b128 v[194:197], v117 offset:0x9000
	v_mfma_f32_32x32x16_bf16 a[128:143], v[88:91], v[52:55], a[128:143]
	ds_read_b128 v[120:123], v115 offset:0x8000
	s_waitcnt lgkmcnt(5)
	v_mfma_f32_32x32x16_bf16 a[144:159], v[92:95], v[44:47], a[144:159]
	ds_read_b128 v[124:127], v115 offset:0x8800
	v_mfma_f32_32x32x16_bf16 a[160:175], v[92:95], v[48:51], a[160:175]
	ds_read_b128 v[128:131], v115 offset:0x9000
	v_mfma_f32_32x32x16_bf16 a[176:191], v[92:95], v[52:55], a[176:191]
	ds_read_b128 v[198:201], v115 offset:0x9800
	s_waitcnt lgkmcnt(7)
	v_mfma_f32_32x32x16_bf16 a[32:47], v[96:99], v[44:47], a[32:47]
	s_waitcnt vmcnt(13)
	ds_write_b128 v118, v[64:67] offset:0
	v_mfma_f32_32x32x16_bf16 a[16:31], v[96:99], v[48:51], a[16:31]
	s_waitcnt vmcnt(12)
	ds_write_b128 v118, v[60:63] offset:0x1000
	v_mfma_f32_32x32x16_bf16 a[0:15], v[96:99], v[52:55], a[0:15]
	s_waitcnt vmcnt(11)
	ds_write_b128 v118, v[72:75] offset:0x2000
	s_waitcnt lgkmcnt(6)
	v_mfma_f32_32x32x16_bf16 a[48:63], v[120:123], v[40:43], a[48:63]
	s_waitcnt vmcnt(10)
	ds_write_b128 v118, v[68:71] offset:0x3000
	v_mfma_f32_32x32x16_bf16 a[64:79], v[120:123], v[36:39], a[64:79]
	s_waitcnt vmcnt(9)
	ds_write_b128 v118, v[84:87] offset:0x4000
	v_mfma_f32_32x32x16_bf16 a[80:95], v[120:123], v[194:197], a[80:95]
	s_waitcnt vmcnt(8)
	ds_write_b128 v118, v[76:79] offset:0x5000
	s_waitcnt lgkmcnt(8)
	v_mfma_f32_32x32x16_bf16 a[96:111], v[124:127], v[40:43], a[96:111]
	s_waitcnt vmcnt(7)
	ds_write_b128 v118, v[80:83] offset:0x6000
	v_mfma_f32_32x32x16_bf16 a[112:127], v[124:127], v[36:39], a[112:127]
	v_mfma_f32_32x32x16_bf16 a[128:143], v[124:127], v[194:197], a[128:143]
	s_waitcnt lgkmcnt(0)
	s_mov_b32 s6, s7
	s_add_i32 s7, s6, 64
	s_min_u32 s8, s7, 0xae0
	s_lshl_b32 s78, s8, 1
.Lrs1_top:
	s_barrier
	ds_read_b128 v[52:55], v116 offset:0
	ds_read_b128 v[48:51], v116 offset:0x800
	ds_read_b128 v[44:47], v116 offset:0x1000
	ds_read_b128 v[96:99], v114 offset:0
	v_mfma_f32_32x32x16_bf16 a[144:159], v[128:131], v[40:43], a[144:159]
	ds_read_b128 v[92:95], v114 offset:0x800
	v_mfma_f32_32x32x16_bf16 a[160:175], v[128:131], v[36:39], a[160:175]
	ds_read_b128 v[88:91], v114 offset:0x1000
	v_add_u32_e32 v142, s78, v140
	v_add_u32_e32 v143, s78, v141
	global_load_dwordx4 v[64:67], v142, s[10:11]
	v_mfma_f32_32x32x16_bf16 a[176:191], v[128:131], v[194:197], a[176:191]
	ds_read_b128 v[56:59], v114 offset:0x1800
	global_load_dwordx4 v[60:63], v142, s[12:13]
	v_mfma_f32_32x32x16_bf16 a[32:47], v[198:201], v[40:43], a[32:47]
	global_load_dwordx4 v[72:75], v142, s[14:15]
	v_mfma_f32_32x32x16_bf16 a[16:31], v[198:201], v[36:39], a[16:31]
	global_load_dwordx4 v[68:71], v142, s[16:17]
	v_mfma_f32_32x32x16_bf16 a[0:15], v[198:201], v[194:197], a[0:15]
	global_load_dwordx4 v[84:87], v143, s[18:19]
	s_waitcnt lgkmcnt(3)
	v_mfma_f32_32x32x16_bf16 a[48:63], v[96:99], v[52:55], a[48:63]
	ds_read_b128 v[36:39], v117 offset:0
	v_mfma_f32_32x32x16_bf16 a[64:79], v[96:99], v[48:51], a[64:79]
	global_load_dwordx4 v[76:79], v143, s[20:21]
	v_mfma_f32_32x32x16_bf16 a[80:95], v[96:99], v[44:47], a[80:95]
	ds_read_b128 v[40:43], v117 offset:0x800
	s_waitcnt lgkmcnt(4)
	v_mfma_f32_32x32x16_bf16 a[96:111], v[92:95], v[52:55], a[96:111]
	global_load_dwordx4 v[80:83], v143, s[22:23]
	v_mfma_f32_32x32x16_bf16 a[112:127], v[92:95], v[48:51], a[112:127]
	ds_read_b128 v[120:123], v117 offset:0x1000
	v_mfma_f32_32x32x16_bf16 a[128:143], v[92:95], v[44:47], a[128:143]
	ds_read_b128 v[124:127], v115 offset:0
	s_waitcnt lgkmcnt(5)
	v_mfma_f32_32x32x16_bf16 a[144:159], v[88:91], v[52:55], a[144:159]
	ds_read_b128 v[128:131], v115 offset:0x800
	s_min_u32 s6, s6, 0xa80
	s_lshl_b32 s78, s6, 1
	v_mfma_f32_32x32x16_bf16 a[160:175], v[88:91], v[48:51], a[160:175]
	ds_read_b128 v[132:135], v115 offset:0x1000
	s_add_i32 s8, s78, 0xc0
	s_mov_b32 s9, s79
	v_mfma_f32_32x32x16_bf16 a[176:191], v[88:91], v[44:47], a[176:191]
	ds_read_b128 v[136:139], v115 offset:0x1800
	s_add_i32 s5, s5, 2
	s_cmpk_lt_u32 s5, 0x54
	s_waitcnt lgkmcnt(7)
	v_mfma_f32_32x32x16_bf16 a[32:47], v[56:59], v[52:55], a[32:47]
	s_waitcnt vmcnt(13)
	ds_write_b128 v118, v[4:7] offset:0x8000
	v_mfma_f32_32x32x16_bf16 a[16:31], v[56:59], v[48:51], a[16:31]
	s_waitcnt vmcnt(12)
	ds_write_b128 v118, v[8:11] offset:0x9000
	v_mfma_f32_32x32x16_bf16 a[0:15], v[56:59], v[44:47], a[0:15]
	s_waitcnt vmcnt(11)
	ds_write_b128 v118, v[12:15] offset:0xa000
	s_waitcnt lgkmcnt(6)
	v_mfma_f32_32x32x16_bf16 a[48:63], v[124:127], v[36:39], a[48:63]
	s_waitcnt vmcnt(10)
	ds_write_b128 v118, v[16:19] offset:0xb000
	v_mfma_f32_32x32x16_bf16 a[64:79], v[124:127], v[40:43], a[64:79]
	s_waitcnt vmcnt(9)
	ds_write_b128 v118, v[20:23] offset:0xc000
	v_mfma_f32_32x32x16_bf16 a[80:95], v[124:127], v[120:123], a[80:95]
	s_waitcnt vmcnt(8)
	ds_write_b128 v118, v[24:27] offset:0xd000
	s_waitcnt lgkmcnt(8)
	v_mfma_f32_32x32x16_bf16 a[96:111], v[128:131], v[36:39], a[96:111]
	s_waitcnt vmcnt(7)
	ds_write_b128 v118, v[28:31] offset:0xe000
	v_mfma_f32_32x32x16_bf16 a[112:127], v[128:131], v[40:43], a[112:127]
	v_mfma_f32_32x32x16_bf16 a[128:143], v[128:131], v[120:123], a[128:143]
	s_waitcnt lgkmcnt(0)
	s_barrier
	ds_read_b128 v[44:47], v116 offset:0x8000
	ds_read_b128 v[48:51], v116 offset:0x8800
	ds_read_b128 v[52:55], v116 offset:0x9000
	ds_read_b128 v[56:59], v114 offset:0x8000
	v_mfma_f32_32x32x16_bf16 a[144:159], v[132:135], v[36:39], a[144:159]
	ds_read_b128 v[88:91], v114 offset:0x8800
	v_mfma_f32_32x32x16_bf16 a[160:175], v[132:135], v[40:43], a[160:175]
	ds_read_b128 v[92:95], v114 offset:0x9000
	v_add_u32_e32 v142, s8, v140
	v_add_u32_e32 v143, s8, v141
	global_load_dwordx4 v[4:7], v142, s[10:11]
	v_mfma_f32_32x32x16_bf16 a[176:191], v[132:135], v[120:123], a[176:191]
	ds_read_b128 v[96:99], v114 offset:0x9800
	global_load_dwordx4 v[8:11], v142, s[12:13]
	v_mfma_f32_32x32x16_bf16 a[32:47], v[136:139], v[36:39], a[32:47]
	global_load_dwordx4 v[12:15], v142, s[14:15]
	v_mfma_f32_32x32x16_bf16 a[16:31], v[136:139], v[40:43], a[16:31]
	global_load_dwordx4 v[16:19], v142, s[16:17]
	v_mfma_f32_32x32x16_bf16 a[0:15], v[136:139], v[120:123], a[0:15]
	global_load_dwordx4 v[20:23], v143, s[18:19]
	s_waitcnt lgkmcnt(3)
	v_mfma_f32_32x32x16_bf16 a[48:63], v[56:59], v[44:47], a[48:63]
	ds_read_b128 v[40:43], v117 offset:0x8000
	v_mfma_f32_32x32x16_bf16 a[64:79], v[56:59], v[48:51], a[64:79]
	global_load_dwordx4 v[24:27], v143, s[20:21]
	v_mfma_f32_32x32x16_bf16 a[80:95], v[56:59], v[52:55], a[80:95]
	ds_read_b128 v[36:39], v117 offset:0x8800
	s_waitcnt lgkmcnt(4)
	v_mfma_f32_32x32x16_bf16 a[96:111], v[88:91], v[44:47], a[96:111]
	global_load_dwordx4 v[28:31], v143, s[22:23]
	v_mfma_f32_32x32x16_bf16 a[112:127], v[88:91], v[48:51], a[112:127]
	ds_read_b128 v[194:197], v117 offset:0x9000
	v_mfma_f32_32x32x16_bf16 a[128:143], v[88:91], v[52:55], a[128:143]
	ds_read_b128 v[120:123], v115 offset:0x8000
	s_waitcnt lgkmcnt(5)
	v_mfma_f32_32x32x16_bf16 a[144:159], v[92:95], v[44:47], a[144:159]
	ds_read_b128 v[124:127], v115 offset:0x8800
	v_mfma_f32_32x32x16_bf16 a[160:175], v[92:95], v[48:51], a[160:175]
	ds_read_b128 v[128:131], v115 offset:0x9000
	v_mfma_f32_32x32x16_bf16 a[176:191], v[92:95], v[52:55], a[176:191]
	ds_read_b128 v[198:201], v115 offset:0x9800
	s_waitcnt lgkmcnt(7)
	v_mfma_f32_32x32x16_bf16 a[32:47], v[96:99], v[44:47], a[32:47]
	s_waitcnt vmcnt(13)
	ds_write_b128 v118, v[64:67] offset:0
	v_mfma_f32_32x32x16_bf16 a[16:31], v[96:99], v[48:51], a[16:31]
	s_waitcnt vmcnt(12)
	ds_write_b128 v118, v[60:63] offset:0x1000
	v_mfma_f32_32x32x16_bf16 a[0:15], v[96:99], v[52:55], a[0:15]
	s_waitcnt vmcnt(11)
	ds_write_b128 v118, v[72:75] offset:0x2000
	s_waitcnt lgkmcnt(6)
	v_mfma_f32_32x32x16_bf16 a[48:63], v[120:123], v[40:43], a[48:63]
	s_waitcnt vmcnt(10)
	ds_write_b128 v118, v[68:71] offset:0x3000
	v_mfma_f32_32x32x16_bf16 a[64:79], v[120:123], v[36:39], a[64:79]
	s_waitcnt vmcnt(9)
	ds_write_b128 v118, v[84:87] offset:0x4000
	v_mfma_f32_32x32x16_bf16 a[80:95], v[120:123], v[194:197], a[80:95]
	s_waitcnt vmcnt(8)
	ds_write_b128 v118, v[76:79] offset:0x5000
	s_waitcnt lgkmcnt(8)
	v_mfma_f32_32x32x16_bf16 a[96:111], v[124:127], v[40:43], a[96:111]
	s_waitcnt vmcnt(7)
	ds_write_b128 v118, v[80:83] offset:0x6000
	v_mfma_f32_32x32x16_bf16 a[112:127], v[124:127], v[36:39], a[112:127]
	v_mfma_f32_32x32x16_bf16 a[128:143], v[124:127], v[194:197], a[128:143]
	s_waitcnt lgkmcnt(0)
	s_cbranch_scc0 .Lrs1_last
	s_mov_b32 s6, s7
	s_add_i32 s7, s6, 64
	s_min_u32 s8, s7, 0xae0
	s_lshl_b32 s78, s8, 1
	s_branch .Lrs1_top
.Lrs1_last:
	s_barrier
	s_mov_b32 s6, s7
	s_add_i32 s7, s6, 64
	s_min_u32 s8, s7, 0xae0
	s_lshl_b32 s78, s8, 1
	ds_read_b128 v[52:55], v116 offset:0
	ds_read_b128 v[48:51], v116 offset:0x800
	ds_read_b128 v[44:47], v116 offset:0x1000
	ds_read_b128 v[96:99], v114 offset:0
	v_mfma_f32_32x32x16_bf16 a[144:159], v[128:131], v[40:43], a[144:159]
	ds_read_b128 v[92:95], v114 offset:0x800
	v_mfma_f32_32x32x16_bf16 a[160:175], v[128:131], v[36:39], a[160:175]
	ds_read_b128 v[88:91], v114 offset:0x1000
	v_mfma_f32_32x32x16_bf16 a[176:191], v[128:131], v[194:197], a[176:191]
	ds_read_b128 v[56:59], v114 offset:0x1800
	v_mfma_f32_32x32x16_bf16 a[32:47], v[198:201], v[40:43], a[32:47]
	v_mfma_f32_32x32x16_bf16 a[16:31], v[198:201], v[36:39], a[16:31]
	v_mfma_f32_32x32x16_bf16 a[0:15], v[198:201], v[194:197], a[0:15]
	s_waitcnt lgkmcnt(3)
	v_mfma_f32_32x32x16_bf16 a[48:63], v[96:99], v[52:55], a[48:63]
	ds_read_b128 v[36:39], v117 offset:0
	v_mfma_f32_32x32x16_bf16 a[64:79], v[96:99], v[48:51], a[64:79]
	v_mfma_f32_32x32x16_bf16 a[80:95], v[96:99], v[44:47], a[80:95]
	ds_read_b128 v[40:43], v117 offset:0x800
	s_waitcnt lgkmcnt(4)
	v_mfma_f32_32x32x16_bf16 a[96:111], v[92:95], v[52:55], a[96:111]
	v_mfma_f32_32x32x16_bf16 a[112:127], v[92:95], v[48:51], a[112:127]
	ds_read_b128 v[120:123], v117 offset:0x1000
	v_mfma_f32_32x32x16_bf16 a[128:143], v[92:95], v[44:47], a[128:143]
	ds_read_b128 v[124:127], v115 offset:0
	s_waitcnt lgkmcnt(5)
	v_mfma_f32_32x32x16_bf16 a[144:159], v[88:91], v[52:55], a[144:159]
	ds_read_b128 v[128:131], v115 offset:0x800
	s_min_u32 s6, s6, 0xa80
	s_lshl_b32 s78, s6, 1
	v_mfma_f32_32x32x16_bf16 a[160:175], v[88:91], v[48:51], a[160:175]
	ds_read_b128 v[132:135], v115 offset:0x1000
	s_add_i32 s8, s78, 0xc0
	s_mov_b32 s9, s79
	v_mfma_f32_32x32x16_bf16 a[176:191], v[88:91], v[44:47], a[176:191]
	ds_read_b128 v[136:139], v115 offset:0x1800
	s_add_i32 s5, s5, 2
	s_cmpk_lt_u32 s5, 0x56
	s_waitcnt lgkmcnt(7)
	v_mfma_f32_32x32x16_bf16 a[32:47], v[56:59], v[52:55], a[32:47]
	s_waitcnt vmcnt(6)
	ds_write_b128 v118, v[4:7] offset:0x8000
	v_mfma_f32_32x32x16_bf16 a[16:31], v[56:59], v[48:51], a[16:31]
	s_waitcnt vmcnt(5)
	ds_write_b128 v118, v[8:11] offset:0x9000
	v_mfma_f32_32x32x16_bf16 a[0:15], v[56:59], v[44:47], a[0:15]
	s_waitcnt vmcnt(4)
	ds_write_b128 v118, v[12:15] offset:0xa000
	s_waitcnt lgkmcnt(6)
	v_mfma_f32_32x32x16_bf16 a[48:63], v[124:127], v[36:39], a[48:63]
	s_waitcnt vmcnt(3)
	ds_write_b128 v118, v[16:19] offset:0xb000
	v_mfma_f32_32x32x16_bf16 a[64:79], v[124:127], v[40:43], a[64:79]
	s_waitcnt vmcnt(2)
	ds_write_b128 v118, v[20:23] offset:0xc000
	v_mfma_f32_32x32x16_bf16 a[80:95], v[124:127], v[120:123], a[80:95]
	s_waitcnt vmcnt(1)
	ds_write_b128 v118, v[24:27] offset:0xd000
	s_waitcnt lgkmcnt(8)
	v_mfma_f32_32x32x16_bf16 a[96:111], v[128:131], v[36:39], a[96:111]
	s_waitcnt vmcnt(0)
	ds_write_b128 v118, v[28:31] offset:0xe000
	v_mfma_f32_32x32x16_bf16 a[112:127], v[128:131], v[40:43], a[112:127]
	v_mfma_f32_32x32x16_bf16 a[128:143], v[128:131], v[120:123], a[128:143]
	s_waitcnt lgkmcnt(0)
	s_barrier
	ds_read_b128 v[44:47], v116 offset:0x8000
	ds_read_b128 v[48:51], v116 offset:0x8800
	ds_read_b128 v[52:55], v116 offset:0x9000
	ds_read_b128 v[56:59], v114 offset:0x8000
	v_mfma_f32_32x32x16_bf16 a[144:159], v[132:135], v[36:39], a[144:159]
	ds_read_b128 v[88:91], v114 offset:0x8800
	v_mfma_f32_32x32x16_bf16 a[160:175], v[132:135], v[40:43], a[160:175]
	ds_read_b128 v[92:95], v114 offset:0x9000
	v_mfma_f32_32x32x16_bf16 a[176:191], v[132:135], v[120:123], a[176:191]
	ds_read_b128 v[96:99], v114 offset:0x9800
	v_mfma_f32_32x32x16_bf16 a[32:47], v[136:139], v[36:39], a[32:47]
	v_mfma_f32_32x32x16_bf16 a[16:31], v[136:139], v[40:43], a[16:31]
	v_mfma_f32_32x32x16_bf16 a[0:15], v[136:139], v[120:123], a[0:15]
	s_waitcnt lgkmcnt(3)
	v_mfma_f32_32x32x16_bf16 a[48:63], v[56:59], v[44:47], a[48:63]
	ds_read_b128 v[40:43], v117 offset:0x8000
	v_mfma_f32_32x32x16_bf16 a[64:79], v[56:59], v[48:51], a[64:79]
	v_mfma_f32_32x32x16_bf16 a[80:95], v[56:59], v[52:55], a[80:95]
	ds_read_b128 v[36:39], v117 offset:0x8800
	s_waitcnt lgkmcnt(4)
	v_mfma_f32_32x32x16_bf16 a[96:111], v[88:91], v[44:47], a[96:111]
	v_mfma_f32_32x32x16_bf16 a[112:127], v[88:91], v[48:51], a[112:127]
	ds_read_b128 v[194:197], v117 offset:0x9000
	v_mfma_f32_32x32x16_bf16 a[128:143], v[88:91], v[52:55], a[128:143]
	ds_read_b128 v[120:123], v115 offset:0x8000
	s_waitcnt lgkmcnt(5)
	v_mfma_f32_32x32x16_bf16 a[144:159], v[92:95], v[44:47], a[144:159]
	ds_read_b128 v[124:127], v115 offset:0x8800
	v_mfma_f32_32x32x16_bf16 a[160:175], v[92:95], v[48:51], a[160:175]
	ds_read_b128 v[128:131], v115 offset:0x9000
	v_mfma_f32_32x32x16_bf16 a[176:191], v[92:95], v[52:55], a[176:191]
	ds_read_b128 v[198:201], v115 offset:0x9800
	s_waitcnt lgkmcnt(7)
	v_mfma_f32_32x32x16_bf16 a[32:47], v[96:99], v[44:47], a[32:47]
	v_mfma_f32_32x32x16_bf16 a[16:31], v[96:99], v[48:51], a[16:31]
	v_mfma_f32_32x32x16_bf16 a[0:15], v[96:99], v[52:55], a[0:15]
	s_waitcnt lgkmcnt(3)
	v_mfma_f32_32x32x16_bf16 a[48:63], v[120:123], v[40:43], a[48:63]
	v_mfma_f32_32x32x16_bf16 a[64:79], v[120:123], v[36:39], a[64:79]
	v_mfma_f32_32x32x16_bf16 a[80:95], v[120:123], v[194:197], a[80:95]
	s_waitcnt lgkmcnt(2)
	v_mfma_f32_32x32x16_bf16 a[96:111], v[124:127], v[40:43], a[96:111]
	v_mfma_f32_32x32x16_bf16 a[112:127], v[124:127], v[36:39], a[112:127]
	v_mfma_f32_32x32x16_bf16 a[128:143], v[124:127], v[194:197], a[128:143]
	s_waitcnt lgkmcnt(0)
	s_barrier
	v_mfma_f32_32x32x16_bf16 a[144:159], v[128:131], v[40:43], a[144:159]
	v_mfma_f32_32x32x16_bf16 a[160:175], v[128:131], v[36:39], a[160:175]
	v_mfma_f32_32x32x16_bf16 a[176:191], v[128:131], v[194:197], a[176:191]
	s_nop 7
	s_nop 3
	s_branch .LBB0_120

.LBB0_141:
	v_readfirstlane_b32 s8, v68
	v_readfirstlane_b32 s9, v69
	v_readfirstlane_b32 s10, v72
	v_readfirstlane_b32 s11, v73
	v_readfirstlane_b32 s12, v74
	v_readfirstlane_b32 s13, v75
	v_readfirstlane_b32 s14, v76
	v_readfirstlane_b32 s15, v77
	v_readfirstlane_b32 s16, v70
	v_readfirstlane_b32 s17, v71
	v_readfirstlane_b32 s18, v78
	v_readfirstlane_b32 s19, v79
	v_subrev_u32_e32 v144, s8, v68
	v_subrev_u32_e32 v145, s16, v70
	s_nop 4
	s_add_i32 s5, s4, 64
	s_min_u32 s6, s5, 0xae0
	s_lshl_b32 s78, s6, 1
	ds_read_b128 v[48:51], v82 offset:0
	ds_read_b128 v[44:47], v82 offset:0x800
	ds_read_b128 v[64:67], v80 offset:0
	ds_read_b128 v[60:63], v80 offset:0x800
	ds_read_b128 v[56:59], v80 offset:0x1000
	v_add_u32_e32 v146, s78, v144
	v_add_u32_e32 v147, s78, v145
	global_load_dwordx4 v[106:109], v146, s[8:9]
	ds_read_b128 v[52:55], v80 offset:0x1800
	global_load_dwordx4 v[110:113], v146, s[10:11]
	global_load_dwordx4 v[114:117], v146, s[12:13]
	s_waitcnt lgkmcnt(3)
	v_mfma_f32_32x32x16_bf16 a[32:47], v[64:67], v[48:51], 0
	ds_read_b128 v[40:43], v83 offset:0
	v_mfma_f32_32x32x16_bf16 a[48:63], v[64:67], v[44:47], 0
	global_load_dwordx4 v[118:121], v146, s[14:15]
	s_waitcnt lgkmcnt(3)
	v_mfma_f32_32x32x16_bf16 a[64:79], v[60:63], v[48:51], 0
	ds_read_b128 v[86:89], v83 offset:0x800
	v_mfma_f32_32x32x16_bf16 a[80:95], v[60:63], v[44:47], 0
	global_load_dwordx4 v[122:125], v147, s[16:17]
	s_waitcnt lgkmcnt(3)
	v_mfma_f32_32x32x16_bf16 a[96:111], v[56:59], v[48:51], 0
	ds_read_b128 v[90:93], v81 offset:0
	v_mfma_f32_32x32x16_bf16 a[112:127], v[56:59], v[44:47], 0
	global_load_dwordx4 v[140:143], v147, s[18:19]
	s_waitcnt vmcnt(11)
	ds_write_b128 v84, v[4:7] offset:0x8000
	s_waitcnt lgkmcnt(4)
	v_mfma_f32_32x32x16_bf16 a[16:31], v[52:55], v[48:51], 0
	ds_read_b128 v[94:97], v81 offset:0x800
	s_min_u32 s4, s4, 0xa80
	s_lshl_b32 s78, s4, 1
	s_waitcnt vmcnt(10)
	ds_write_b128 v84, v[8:11] offset:0x9000
	v_mfma_f32_32x32x16_bf16 a[0:15], v[52:55], v[44:47], 0
	ds_read_b128 v[98:101], v81 offset:0x1000
	s_add_i32 s6, s78, 0xc0
	s_mov_b32 s7, s79
	s_waitcnt vmcnt(9)
	ds_write_b128 v84, v[12:15] offset:0xa000
	s_waitcnt lgkmcnt(5)
	v_mfma_f32_32x32x16_bf16 a[32:47], v[90:93], v[40:43], a[32:47]
	ds_read_b128 v[102:105], v81 offset:0x1800
	s_add_i32 s3, s3, 2
	s_cmpk_lt_u32 s3, 0x56
	s_waitcnt vmcnt(8)
	ds_write_b128 v84, v[16:19] offset:0xb000
	v_mfma_f32_32x32x16_bf16 a[48:63], v[90:93], v[86:89], a[48:63]
	s_waitcnt vmcnt(7)
	ds_write_b128 v84, v[20:23] offset:0xc000
	s_waitcnt lgkmcnt(6)
	v_mfma_f32_32x32x16_bf16 a[64:79], v[94:97], v[40:43], a[64:79]
	s_waitcnt vmcnt(6)
	ds_write_b128 v84, v[24:27] offset:0xd000
	v_mfma_f32_32x32x16_bf16 a[80:95], v[94:97], v[86:89], a[80:95]
	s_waitcnt lgkmcnt(0)
	s_barrier
	ds_read_b128 v[44:47], v82 offset:0x8000
	ds_read_b128 v[48:51], v82 offset:0x8800
	ds_read_b128 v[52:55], v80 offset:0x8000
	v_mfma_f32_32x32x16_bf16 a[96:111], v[98:101], v[40:43], a[96:111]
	ds_read_b128 v[56:59], v80 offset:0x8800
	v_mfma_f32_32x32x16_bf16 a[112:127], v[98:101], v[86:89], a[112:127]
	ds_read_b128 v[60:63], v80 offset:0x9000
	v_add_u32_e32 v146, s6, v144
	v_add_u32_e32 v147, s6, v145
	global_load_dwordx4 v[4:7], v146, s[8:9]
	v_mfma_f32_32x32x16_bf16 a[16:31], v[102:105], v[40:43], a[16:31]
	ds_read_b128 v[64:67], v80 offset:0x9800
	global_load_dwordx4 v[8:11], v146, s[10:11]
	v_mfma_f32_32x32x16_bf16 a[0:15], v[102:105], v[86:89], a[0:15]
	global_load_dwordx4 v[12:15], v146, s[12:13]
	s_waitcnt lgkmcnt(3)
	v_mfma_f32_32x32x16_bf16 a[32:47], v[52:55], v[44:47], a[32:47]
	ds_read_b128 v[40:43], v83 offset:0x8000
	v_mfma_f32_32x32x16_bf16 a[48:63], v[52:55], v[48:51], a[48:63]
	global_load_dwordx4 v[16:19], v146, s[14:15]
	s_waitcnt lgkmcnt(3)
	v_mfma_f32_32x32x16_bf16 a[64:79], v[56:59], v[44:47], a[64:79]
	ds_read_b128 v[128:131], v83 offset:0x8800
	v_mfma_f32_32x32x16_bf16 a[80:95], v[56:59], v[48:51], a[80:95]
	global_load_dwordx4 v[20:23], v147, s[16:17]
	s_waitcnt lgkmcnt(3)
	v_mfma_f32_32x32x16_bf16 a[96:111], v[60:63], v[44:47], a[96:111]
	ds_read_b128 v[86:89], v81 offset:0x8000
	v_mfma_f32_32x32x16_bf16 a[112:127], v[60:63], v[48:51], a[112:127]
	global_load_dwordx4 v[24:27], v147, s[18:19]
	s_waitcnt vmcnt(11)
	ds_write_b128 v84, v[106:109] offset:0
	s_waitcnt lgkmcnt(4)
	v_mfma_f32_32x32x16_bf16 a[16:31], v[64:67], v[44:47], a[16:31]
	ds_read_b128 v[90:93], v81 offset:0x8800
	s_waitcnt vmcnt(10)
	ds_write_b128 v84, v[110:113] offset:0x1000
	v_mfma_f32_32x32x16_bf16 a[0:15], v[64:67], v[48:51], a[0:15]
	ds_read_b128 v[94:97], v81 offset:0x9000
	s_waitcnt vmcnt(9)
	ds_write_b128 v84, v[114:117] offset:0x2000
	s_waitcnt lgkmcnt(5)
	v_mfma_f32_32x32x16_bf16 a[32:47], v[86:89], v[40:43], a[32:47]
	ds_read_b128 v[132:135], v81 offset:0x9800
	s_waitcnt vmcnt(8)
	ds_write_b128 v84, v[118:121] offset:0x3000
	v_mfma_f32_32x32x16_bf16 a[48:63], v[86:89], v[128:131], a[48:63]
	s_waitcnt vmcnt(7)
	ds_write_b128 v84, v[122:125] offset:0x4000
	s_waitcnt lgkmcnt(6)
	v_mfma_f32_32x32x16_bf16 a[64:79], v[90:93], v[40:43], a[64:79]
	s_waitcnt vmcnt(6)
	ds_write_b128 v84, v[140:143] offset:0x5000
	v_mfma_f32_32x32x16_bf16 a[80:95], v[90:93], v[128:131], a[80:95]
	s_waitcnt lgkmcnt(0)
	s_mov_b32 s4, s5
	s_add_i32 s5, s4, 64
	s_min_u32 s6, s5, 0xae0
	s_lshl_b32 s78, s6, 1
.Lrs2_top:
	s_barrier
	ds_read_b128 v[48:51], v82 offset:0
	ds_read_b128 v[44:47], v82 offset:0x800
	ds_read_b128 v[64:67], v80 offset:0
	v_mfma_f32_32x32x16_bf16 a[96:111], v[94:97], v[40:43], a[96:111]
	ds_read_b128 v[60:63], v80 offset:0x800
	v_mfma_f32_32x32x16_bf16 a[112:127], v[94:97], v[128:131], a[112:127]
	ds_read_b128 v[56:59], v80 offset:0x1000
	v_add_u32_e32 v146, s78, v144
	v_add_u32_e32 v147, s78, v145
	global_load_dwordx4 v[106:109], v146, s[8:9]
	v_mfma_f32_32x32x16_bf16 a[16:31], v[132:135], v[40:43], a[16:31]
	ds_read_b128 v[52:55], v80 offset:0x1800
	global_load_dwordx4 v[110:113], v146, s[10:11]
	v_mfma_f32_32x32x16_bf16 a[0:15], v[132:135], v[128:131], a[0:15]
	global_load_dwordx4 v[114:117], v146, s[12:13]
	s_waitcnt lgkmcnt(3)
	v_mfma_f32_32x32x16_bf16 a[32:47], v[64:67], v[48:51], a[32:47]
	ds_read_b128 v[40:43], v83 offset:0
	v_mfma_f32_32x32x16_bf16 a[48:63], v[64:67], v[44:47], a[48:63]
	global_load_dwordx4 v[118:121], v146, s[14:15]
	s_waitcnt lgkmcnt(3)
	v_mfma_f32_32x32x16_bf16 a[64:79], v[60:63], v[48:51], a[64:79]
	ds_read_b128 v[86:89], v83 offset:0x800
	v_mfma_f32_32x32x16_bf16 a[80:95], v[60:63], v[44:47], a[80:95]
	global_load_dwordx4 v[122:125], v147, s[16:17]
	s_waitcnt lgkmcnt(3)
	v_mfma_f32_32x32x16_bf16 a[96:111], v[56:59], v[48:51], a[96:111]
	ds_read_b128 v[90:93], v81 offset:0
	v_mfma_f32_32x32x16_bf16 a[112:127], v[56:59], v[44:47], a[112:127]
	global_load_dwordx4 v[140:143], v147, s[18:19]
	s_waitcnt vmcnt(11)
	ds_write_b128 v84, v[4:7] offset:0x8000
	s_waitcnt lgkmcnt(4)
	v_mfma_f32_32x32x16_bf16 a[16:31], v[52:55], v[48:51], a[16:31]
	ds_read_b128 v[94:97], v81 offset:0x800
	s_min_u32 s4, s4, 0xa80
	s_lshl_b32 s78, s4, 1
	s_waitcnt vmcnt(10)
	ds_write_b128 v84, v[8:11] offset:0x9000
	v_mfma_f32_32x32x16_bf16 a[0:15], v[52:55], v[44:47], a[0:15]
	ds_read_b128 v[98:101], v81 offset:0x1000
	s_add_i32 s6, s78, 0xc0
	s_mov_b32 s7, s79
	s_waitcnt vmcnt(9)
	ds_write_b128 v84, v[12:15] offset:0xa000
	s_waitcnt lgkmcnt(5)
	v_mfma_f32_32x32x16_bf16 a[32:47], v[90:93], v[40:43], a[32:47]
	ds_read_b128 v[102:105], v81 offset:0x1800
	s_add_i32 s3, s3, 2
	s_cmpk_lt_u32 s3, 0x54
	s_waitcnt vmcnt(8)
	ds_write_b128 v84, v[16:19] offset:0xb000
	v_mfma_f32_32x32x16_bf16 a[48:63], v[90:93], v[86:89], a[48:63]
	s_waitcnt vmcnt(7)
	ds_write_b128 v84, v[20:23] offset:0xc000
	s_waitcnt lgkmcnt(6)
	v_mfma_f32_32x32x16_bf16 a[64:79], v[94:97], v[40:43], a[64:79]
	s_waitcnt vmcnt(6)
	ds_write_b128 v84, v[24:27] offset:0xd000
	v_mfma_f32_32x32x16_bf16 a[80:95], v[94:97], v[86:89], a[80:95]
	s_waitcnt lgkmcnt(0)
	s_barrier
	ds_read_b128 v[44:47], v82 offset:0x8000
	ds_read_b128 v[48:51], v82 offset:0x8800
	ds_read_b128 v[52:55], v80 offset:0x8000
	v_mfma_f32_32x32x16_bf16 a[96:111], v[98:101], v[40:43], a[96:111]
	ds_read_b128 v[56:59], v80 offset:0x8800
	v_mfma_f32_32x32x16_bf16 a[112:127], v[98:101], v[86:89], a[112:127]
	ds_read_b128 v[60:63], v80 offset:0x9000
	v_add_u32_e32 v146, s6, v144
	v_add_u32_e32 v147, s6, v145
	global_load_dwordx4 v[4:7], v146, s[8:9]
	v_mfma_f32_32x32x16_bf16 a[16:31], v[102:105], v[40:43], a[16:31]
	ds_read_b128 v[64:67], v80 offset:0x9800
	global_load_dwordx4 v[8:11], v146, s[10:11]
	v_mfma_f32_32x32x16_bf16 a[0:15], v[102:105], v[86:89], a[0:15]
	global_load_dwordx4 v[12:15], v146, s[12:13]
	s_waitcnt lgkmcnt(3)
	v_mfma_f32_32x32x16_bf16 a[32:47], v[52:55], v[44:47], a[32:47]
	ds_read_b128 v[40:43], v83 offset:0x8000
	v_mfma_f32_32x32x16_bf16 a[48:63], v[52:55], v[48:51], a[48:63]
	global_load_dwordx4 v[16:19], v146, s[14:15]
	s_waitcnt lgkmcnt(3)
	v_mfma_f32_32x32x16_bf16 a[64:79], v[56:59], v[44:47], a[64:79]
	ds_read_b128 v[128:131], v83 offset:0x8800
	v_mfma_f32_32x32x16_bf16 a[80:95], v[56:59], v[48:51], a[80:95]
	global_load_dwordx4 v[20:23], v147, s[16:17]
	s_waitcnt lgkmcnt(3)
	v_mfma_f32_32x32x16_bf16 a[96:111], v[60:63], v[44:47], a[96:111]
	ds_read_b128 v[86:89], v81 offset:0x8000
	v_mfma_f32_32x32x16_bf16 a[112:127], v[60:63], v[48:51], a[112:127]
	global_load_dwordx4 v[24:27], v147, s[18:19]
	s_waitcnt vmcnt(11)
	ds_write_b128 v84, v[106:109] offset:0
	s_waitcnt lgkmcnt(4)
	v_mfma_f32_32x32x16_bf16 a[16:31], v[64:67], v[44:47], a[16:31]
	ds_read_b128 v[90:93], v81 offset:0x8800
	s_waitcnt vmcnt(10)
	ds_write_b128 v84, v[110:113] offset:0x1000
	v_mfma_f32_32x32x16_bf16 a[0:15], v[64:67], v[48:51], a[0:15]
	ds_read_b128 v[94:97], v81 offset:0x9000
	s_waitcnt vmcnt(9)
	ds_write_b128 v84, v[114:117] offset:0x2000
	s_waitcnt lgkmcnt(5)
	v_mfma_f32_32x32x16_bf16 a[32:47], v[86:89], v[40:43], a[32:47]
	ds_read_b128 v[132:135], v81 offset:0x9800
	s_waitcnt vmcnt(8)
	ds_write_b128 v84, v[118:121] offset:0x3000
	v_mfma_f32_32x32x16_bf16 a[48:63], v[86:89], v[128:131], a[48:63]
	s_waitcnt vmcnt(7)
	ds_write_b128 v84, v[122:125] offset:0x4000
	s_waitcnt lgkmcnt(6)
	v_mfma_f32_32x32x16_bf16 a[64:79], v[90:93], v[40:43], a[64:79]
	s_waitcnt vmcnt(6)
	ds_write_b128 v84, v[140:143] offset:0x5000
	v_mfma_f32_32x32x16_bf16 a[80:95], v[90:93], v[128:131], a[80:95]
	s_waitcnt lgkmcnt(0)
	s_cbranch_scc0 .Lrs2_last
	s_mov_b32 s4, s5
	s_add_i32 s5, s4, 64
	s_min_u32 s6, s5, 0xae0
	s_lshl_b32 s78, s6, 1
	s_branch .Lrs2_top
.Lrs2_last:
	s_barrier
	s_mov_b32 s4, s5
	s_add_i32 s5, s4, 64
	s_min_u32 s6, s5, 0xae0
	s_lshl_b32 s78, s6, 1
	ds_read_b128 v[48:51], v82 offset:0
	ds_read_b128 v[44:47], v82 offset:0x800
	ds_read_b128 v[64:67], v80 offset:0
	v_mfma_f32_32x32x16_bf16 a[96:111], v[94:97], v[40:43], a[96:111]
	ds_read_b128 v[60:63], v80 offset:0x800
	v_mfma_f32_32x32x16_bf16 a[112:127], v[94:97], v[128:131], a[112:127]
	ds_read_b128 v[56:59], v80 offset:0x1000
	v_mfma_f32_32x32x16_bf16 a[16:31], v[132:135], v[40:43], a[16:31]
	ds_read_b128 v[52:55], v80 offset:0x1800
	v_mfma_f32_32x32x16_bf16 a[0:15], v[132:135], v[128:131], a[0:15]
	s_waitcnt lgkmcnt(3)
	v_mfma_f32_32x32x16_bf16 a[32:47], v[64:67], v[48:51], a[32:47]
	ds_read_b128 v[40:43], v83 offset:0
	v_mfma_f32_32x32x16_bf16 a[48:63], v[64:67], v[44:47], a[48:63]
	s_waitcnt lgkmcnt(3)
	v_mfma_f32_32x32x16_bf16 a[64:79], v[60:63], v[48:51], a[64:79]
	ds_read_b128 v[86:89], v83 offset:0x800
	v_mfma_f32_32x32x16_bf16 a[80:95], v[60:63], v[44:47], a[80:95]
	s_waitcnt lgkmcnt(3)
	v_mfma_f32_32x32x16_bf16 a[96:111], v[56:59], v[48:51], a[96:111]
	ds_read_b128 v[90:93], v81 offset:0
	v_mfma_f32_32x32x16_bf16 a[112:127], v[56:59], v[44:47], a[112:127]
	s_waitcnt vmcnt(5)
	ds_write_b128 v84, v[4:7] offset:0x8000
	s_waitcnt lgkmcnt(4)
	v_mfma_f32_32x32x16_bf16 a[16:31], v[52:55], v[48:51], a[16:31]
	ds_read_b128 v[94:97], v81 offset:0x800
	s_min_u32 s4, s4, 0xa80
	s_lshl_b32 s78, s4, 1
	s_waitcnt vmcnt(4)
	ds_write_b128 v84, v[8:11] offset:0x9000
	v_mfma_f32_32x32x16_bf16 a[0:15], v[52:55], v[44:47], a[0:15]
	ds_read_b128 v[98:101], v81 offset:0x1000
	s_add_i32 s6, s78, 0xc0
	s_mov_b32 s7, s79
	s_waitcnt vmcnt(3)
	ds_write_b128 v84, v[12:15] offset:0xa000
	s_waitcnt lgkmcnt(5)
	v_mfma_f32_32x32x16_bf16 a[32:47], v[90:93], v[40:43], a[32:47]
	ds_read_b128 v[102:105], v81 offset:0x1800
	s_add_i32 s3, s3, 2
	s_cmpk_lt_u32 s3, 0x56
	s_waitcnt vmcnt(2)
	ds_write_b128 v84, v[16:19] offset:0xb000
	v_mfma_f32_32x32x16_bf16 a[48:63], v[90:93], v[86:89], a[48:63]
	s_waitcnt vmcnt(1)
	ds_write_b128 v84, v[20:23] offset:0xc000
	s_waitcnt lgkmcnt(6)
	v_mfma_f32_32x32x16_bf16 a[64:79], v[94:97], v[40:43], a[64:79]
	s_waitcnt vmcnt(0)
	ds_write_b128 v84, v[24:27] offset:0xd000
	v_mfma_f32_32x32x16_bf16 a[80:95], v[94:97], v[86:89], a[80:95]
	s_waitcnt lgkmcnt(0)
	s_barrier
	ds_read_b128 v[44:47], v82 offset:0x8000
	ds_read_b128 v[48:51], v82 offset:0x8800
	ds_read_b128 v[52:55], v80 offset:0x8000
	v_mfma_f32_32x32x16_bf16 a[96:111], v[98:101], v[40:43], a[96:111]
	ds_read_b128 v[56:59], v80 offset:0x8800
	v_mfma_f32_32x32x16_bf16 a[112:127], v[98:101], v[86:89], a[112:127]
	ds_read_b128 v[60:63], v80 offset:0x9000
	v_mfma_f32_32x32x16_bf16 a[16:31], v[102:105], v[40:43], a[16:31]
	ds_read_b128 v[64:67], v80 offset:0x9800
	v_mfma_f32_32x32x16_bf16 a[0:15], v[102:105], v[86:89], a[0:15]
	s_waitcnt lgkmcnt(3)
	v_mfma_f32_32x32x16_bf16 a[32:47], v[52:55], v[44:47], a[32:47]
	ds_read_b128 v[40:43], v83 offset:0x8000
	v_mfma_f32_32x32x16_bf16 a[48:63], v[52:55], v[48:51], a[48:63]
	s_waitcnt lgkmcnt(3)
	v_mfma_f32_32x32x16_bf16 a[64:79], v[56:59], v[44:47], a[64:79]
	ds_read_b128 v[128:131], v83 offset:0x8800
	v_mfma_f32_32x32x16_bf16 a[80:95], v[56:59], v[48:51], a[80:95]
	s_waitcnt lgkmcnt(3)
	v_mfma_f32_32x32x16_bf16 a[96:111], v[60:63], v[44:47], a[96:111]
	ds_read_b128 v[86:89], v81 offset:0x8000
	v_mfma_f32_32x32x16_bf16 a[112:127], v[60:63], v[48:51], a[112:127]
	s_waitcnt lgkmcnt(3)
	v_mfma_f32_32x32x16_bf16 a[16:31], v[64:67], v[44:47], a[16:31]
	ds_read_b128 v[90:93], v81 offset:0x8800
	v_mfma_f32_32x32x16_bf16 a[0:15], v[64:67], v[48:51], a[0:15]
	ds_read_b128 v[94:97], v81 offset:0x9000
	s_waitcnt lgkmcnt(2)
	v_mfma_f32_32x32x16_bf16 a[32:47], v[86:89], v[40:43], a[32:47]
	ds_read_b128 v[132:135], v81 offset:0x9800
	v_mfma_f32_32x32x16_bf16 a[48:63], v[86:89], v[128:131], a[48:63]
	s_waitcnt lgkmcnt(2)
	v_mfma_f32_32x32x16_bf16 a[64:79], v[90:93], v[40:43], a[64:79]
	v_mfma_f32_32x32x16_bf16 a[80:95], v[90:93], v[128:131], a[80:95]
	s_waitcnt lgkmcnt(0)
	s_barrier
	v_mfma_f32_32x32x16_bf16 a[96:111], v[94:97], v[40:43], a[96:111]
	v_mfma_f32_32x32x16_bf16 a[112:127], v[94:97], v[128:131], a[112:127]
	s_nop 7
	s_nop 3
	s_branch .LBB0_139

.LBB0_162:
	v_readfirstlane_b32 s8, v96
	v_readfirstlane_b32 s9, v97
	v_readfirstlane_b32 s10, v100
	v_readfirstlane_b32 s11, v101
	v_readfirstlane_b32 s12, v102
	v_readfirstlane_b32 s13, v103
	v_readfirstlane_b32 s14, v104
	v_readfirstlane_b32 s15, v105
	v_readfirstlane_b32 s16, v98
	v_readfirstlane_b32 s17, v99
	v_readfirstlane_b32 s18, v106
	v_readfirstlane_b32 s19, v107
	v_readfirstlane_b32 s20, v108
	v_readfirstlane_b32 s21, v109
	v_subrev_u32_e32 v140, s8, v96
	v_subrev_u32_e32 v141, s16, v98
	s_nop 4
	s_add_i32 s5, s4, 64
	s_min_u32 s6, s5, 0x3e0
	s_lshl_b32 s78, s6, 1
	ds_read_b128 v[44:47], v116 offset:0
	ds_read_b128 v[40:43], v116 offset:0x800
	ds_read_b128 v[36:39], v116 offset:0x1000
	ds_read_b128 v[92:95], v110 offset:0
	ds_read_b128 v[88:91], v110 offset:0x800
	ds_read_b128 v[84:87], v110 offset:0x1000
	v_add_u32_e32 v142, s78, v140
	v_add_u32_e32 v143, s78, v141
	global_load_dwordx4 v[56:59], v142, s[8:9]
	ds_read_b128 v[48:51], v110 offset:0x1800
	global_load_dwordx4 v[52:55], v142, s[10:11]
	global_load_dwordx4 v[64:67], v142, s[12:13]
	global_load_dwordx4 v[60:63], v142, s[14:15]
	global_load_dwordx4 v[76:79], v143, s[16:17]
	s_waitcnt lgkmcnt(3)
	v_mfma_f32_32x32x16_bf16 a[80:95], v[92:95], v[44:47], 0
	ds_read_b128 v[80:83], v117 offset:0
	v_mfma_f32_32x32x16_bf16 a[48:63], v[92:95], v[40:43], 0
	global_load_dwordx4 v[68:71], v143, s[18:19]
	v_mfma_f32_32x32x16_bf16 a[64:79], v[92:95], v[36:39], 0
	ds_read_b128 v[112:115], v117 offset:0x800
	s_waitcnt lgkmcnt(4)
	v_mfma_f32_32x32x16_bf16 a[96:111], v[88:91], v[44:47], 0
	global_load_dwordx4 v[72:75], v143, s[20:21]
	v_mfma_f32_32x32x16_bf16 a[112:127], v[88:91], v[40:43], 0
	ds_read_b128 v[120:123], v117 offset:0x1000
	v_mfma_f32_32x32x16_bf16 a[128:143], v[88:91], v[36:39], 0
	ds_read_b128 v[124:127], v111 offset:0
	s_waitcnt lgkmcnt(5)
	v_mfma_f32_32x32x16_bf16 a[144:159], v[84:87], v[44:47], 0
	ds_read_b128 v[128:131], v111 offset:0x800
	s_min_u32 s4, s4, 0x380
	s_lshl_b32 s78, s4, 1
	v_mfma_f32_32x32x16_bf16 a[160:175], v[84:87], v[40:43], 0
	ds_read_b128 v[132:135], v111 offset:0x1000
	s_add_i32 s6, s78, 0xc0
	s_mov_b32 s7, s79
	v_mfma_f32_32x32x16_bf16 a[176:191], v[84:87], v[36:39], 0
	ds_read_b128 v[136:139], v111 offset:0x1800
	s_add_i32 s3, s3, 2
	s_cmp_lt_u32 s3, 30
	s_waitcnt lgkmcnt(7)
	v_mfma_f32_32x32x16_bf16 a[32:47], v[48:51], v[44:47], 0
	s_waitcnt vmcnt(13)
	ds_write_b128 v118, v[4:7] offset:0x8000
	v_mfma_f32_32x32x16_bf16 a[16:31], v[48:51], v[40:43], 0
	s_waitcnt vmcnt(12)
	ds_write_b128 v118, v[8:11] offset:0x9000
	v_mfma_f32_32x32x16_bf16 a[0:15], v[48:51], v[36:39], 0
	s_waitcnt vmcnt(11)
	ds_write_b128 v118, v[12:15] offset:0xa000
	s_waitcnt lgkmcnt(6)
	v_mfma_f32_32x32x16_bf16 a[80:95], v[124:127], v[80:83], a[80:95]
	s_waitcnt vmcnt(10)
	ds_write_b128 v118, v[16:19] offset:0xb000
	v_mfma_f32_32x32x16_bf16 a[48:63], v[124:127], v[112:115], a[48:63]
	s_waitcnt vmcnt(9)
	ds_write_b128 v118, v[20:23] offset:0xc000
	v_mfma_f32_32x32x16_bf16 a[64:79], v[124:127], v[120:123], a[64:79]
	s_waitcnt vmcnt(8)
	ds_write_b128 v118, v[24:27] offset:0xd000
	s_waitcnt lgkmcnt(8)
	v_mfma_f32_32x32x16_bf16 a[96:111], v[128:131], v[80:83], a[96:111]
	s_waitcnt vmcnt(7)
	ds_write_b128 v118, v[28:31] offset:0xe000
	v_mfma_f32_32x32x16_bf16 a[112:127], v[128:131], v[112:115], a[112:127]
	v_mfma_f32_32x32x16_bf16 a[128:143], v[128:131], v[120:123], a[128:143]
	s_waitcnt lgkmcnt(0)
	s_barrier
	ds_read_b128 v[36:39], v116 offset:0x8000
	ds_read_b128 v[40:43], v116 offset:0x8800
	ds_read_b128 v[44:47], v116 offset:0x9000
	ds_read_b128 v[48:51], v110 offset:0x8000
	v_mfma_f32_32x32x16_bf16 a[144:159], v[132:135], v[80:83], a[144:159]
	ds_read_b128 v[84:87], v110 offset:0x8800
	v_mfma_f32_32x32x16_bf16 a[160:175], v[132:135], v[112:115], a[160:175]
	ds_read_b128 v[88:91], v110 offset:0x9000
	v_add_u32_e32 v142, s6, v140
	v_add_u32_e32 v143, s6, v141
	global_load_dwordx4 v[4:7], v142, s[8:9]
	v_mfma_f32_32x32x16_bf16 a[176:191], v[132:135], v[120:123], a[176:191]
	ds_read_b128 v[92:95], v110 offset:0x9800
	global_load_dwordx4 v[8:11], v142, s[10:11]
	v_mfma_f32_32x32x16_bf16 a[32:47], v[136:139], v[80:83], a[32:47]
	global_load_dwordx4 v[12:15], v142, s[12:13]
	v_mfma_f32_32x32x16_bf16 a[16:31], v[136:139], v[112:115], a[16:31]
	global_load_dwordx4 v[16:19], v142, s[14:15]
	v_mfma_f32_32x32x16_bf16 a[0:15], v[136:139], v[120:123], a[0:15]
	global_load_dwordx4 v[20:23], v143, s[16:17]
	s_waitcnt lgkmcnt(3)
	v_mfma_f32_32x32x16_bf16 a[80:95], v[48:51], v[36:39], a[80:95]
	ds_read_b128 v[80:83], v117 offset:0x8000
	v_mfma_f32_32x32x16_bf16 a[48:63], v[48:51], v[40:43], a[48:63]
	global_load_dwordx4 v[24:27], v143, s[18:19]
	v_mfma_f32_32x32x16_bf16 a[64:79], v[48:51], v[44:47], a[64:79]
	ds_read_b128 v[112:115], v117 offset:0x8800
	s_waitcnt lgkmcnt(4)
	v_mfma_f32_32x32x16_bf16 a[96:111], v[84:87], v[36:39], a[96:111]
	global_load_dwordx4 v[28:31], v143, s[20:21]
	v_mfma_f32_32x32x16_bf16 a[112:127], v[84:87], v[40:43], a[112:127]
	ds_read_b128 v[128:131], v117 offset:0x9000
	v_mfma_f32_32x32x16_bf16 a[128:143], v[84:87], v[44:47], a[128:143]
	ds_read_b128 v[120:123], v111 offset:0x8000
	s_waitcnt lgkmcnt(5)
	v_mfma_f32_32x32x16_bf16 a[144:159], v[88:91], v[36:39], a[144:159]
	ds_read_b128 v[124:127], v111 offset:0x8800
	v_mfma_f32_32x32x16_bf16 a[160:175], v[88:91], v[40:43], a[160:175]
	ds_read_b128 v[136:139], v111 offset:0x9000
	v_mfma_f32_32x32x16_bf16 a[176:191], v[88:91], v[44:47], a[176:191]
	ds_read_b128 v[132:135], v111 offset:0x9800
	s_waitcnt lgkmcnt(7)
	v_mfma_f32_32x32x16_bf16 a[32:47], v[92:95], v[36:39], a[32:47]
	s_waitcnt vmcnt(13)
	ds_write_b128 v118, v[56:59] offset:0
	v_mfma_f32_32x32x16_bf16 a[16:31], v[92:95], v[40:43], a[16:31]
	s_waitcnt vmcnt(12)
	ds_write_b128 v118, v[52:55] offset:0x1000
	v_mfma_f32_32x32x16_bf16 a[0:15], v[92:95], v[44:47], a[0:15]
	s_waitcnt vmcnt(11)
	ds_write_b128 v118, v[64:67] offset:0x2000
	s_waitcnt lgkmcnt(6)
	v_mfma_f32_32x32x16_bf16 a[80:95], v[120:123], v[80:83], a[80:95]
	s_waitcnt vmcnt(10)
	ds_write_b128 v118, v[60:63] offset:0x3000
	v_mfma_f32_32x32x16_bf16 a[48:63], v[120:123], v[112:115], a[48:63]
	s_waitcnt vmcnt(9)
	ds_write_b128 v118, v[76:79] offset:0x4000
	v_mfma_f32_32x32x16_bf16 a[64:79], v[120:123], v[128:131], a[64:79]
	s_waitcnt vmcnt(8)
	ds_write_b128 v118, v[68:71] offset:0x5000
	s_waitcnt lgkmcnt(8)
	v_mfma_f32_32x32x16_bf16 a[96:111], v[124:127], v[80:83], a[96:111]
	s_waitcnt vmcnt(7)
	ds_write_b128 v118, v[72:75] offset:0x6000
	v_mfma_f32_32x32x16_bf16 a[112:127], v[124:127], v[112:115], a[112:127]
	v_mfma_f32_32x32x16_bf16 a[128:143], v[124:127], v[128:131], a[128:143]
	s_waitcnt lgkmcnt(0)
	s_mov_b32 s4, s5
	s_add_i32 s5, s4, 64
	s_min_u32 s6, s5, 0x3e0
	s_lshl_b32 s78, s6, 1
.Lrs0_top:
	s_barrier
	ds_read_b128 v[44:47], v116 offset:0
	ds_read_b128 v[40:43], v116 offset:0x800
	ds_read_b128 v[36:39], v116 offset:0x1000
	ds_read_b128 v[92:95], v110 offset:0
	v_mfma_f32_32x32x16_bf16 a[144:159], v[136:139], v[80:83], a[144:159]
	ds_read_b128 v[88:91], v110 offset:0x800
	v_mfma_f32_32x32x16_bf16 a[160:175], v[136:139], v[112:115], a[160:175]
	ds_read_b128 v[84:87], v110 offset:0x1000
	v_add_u32_e32 v142, s78, v140
	v_add_u32_e32 v143, s78, v141
	global_load_dwordx4 v[56:59], v142, s[8:9]
	v_mfma_f32_32x32x16_bf16 a[176:191], v[136:139], v[128:131], a[176:191]
	ds_read_b128 v[48:51], v110 offset:0x1800
	global_load_dwordx4 v[52:55], v142, s[10:11]
	v_mfma_f32_32x32x16_bf16 a[32:47], v[132:135], v[80:83], a[32:47]
	global_load_dwordx4 v[64:67], v142, s[12:13]
	v_mfma_f32_32x32x16_bf16 a[16:31], v[132:135], v[112:115], a[16:31]
	global_load_dwordx4 v[60:63], v142, s[14:15]
	v_mfma_f32_32x32x16_bf16 a[0:15], v[132:135], v[128:131], a[0:15]
	global_load_dwordx4 v[76:79], v143, s[16:17]
	s_waitcnt lgkmcnt(3)
	v_mfma_f32_32x32x16_bf16 a[80:95], v[92:95], v[44:47], a[80:95]
	ds_read_b128 v[80:83], v117 offset:0
	v_mfma_f32_32x32x16_bf16 a[48:63], v[92:95], v[40:43], a[48:63]
	global_load_dwordx4 v[68:71], v143, s[18:19]
	v_mfma_f32_32x32x16_bf16 a[64:79], v[92:95], v[36:39], a[64:79]
	ds_read_b128 v[112:115], v117 offset:0x800
	s_waitcnt lgkmcnt(4)
	v_mfma_f32_32x32x16_bf16 a[96:111], v[88:91], v[44:47], a[96:111]
	global_load_dwordx4 v[72:75], v143, s[20:21]
	v_mfma_f32_32x32x16_bf16 a[112:127], v[88:91], v[40:43], a[112:127]
	ds_read_b128 v[120:123], v117 offset:0x1000
	v_mfma_f32_32x32x16_bf16 a[128:143], v[88:91], v[36:39], a[128:143]
	ds_read_b128 v[124:127], v111 offset:0
	s_waitcnt lgkmcnt(5)
	v_mfma_f32_32x32x16_bf16 a[144:159], v[84:87], v[44:47], a[144:159]
	ds_read_b128 v[128:131], v111 offset:0x800
	s_min_u32 s4, s4, 0x380
	s_lshl_b32 s78, s4, 1
	v_mfma_f32_32x32x16_bf16 a[160:175], v[84:87], v[40:43], a[160:175]
	ds_read_b128 v[132:135], v111 offset:0x1000
	s_add_i32 s6, s78, 0xc0
	s_mov_b32 s7, s79
	v_mfma_f32_32x32x16_bf16 a[176:191], v[84:87], v[36:39], a[176:191]
	ds_read_b128 v[136:139], v111 offset:0x1800
	s_add_i32 s3, s3, 2
	s_cmp_lt_u32 s3, 28
	s_waitcnt lgkmcnt(7)
	v_mfma_f32_32x32x16_bf16 a[32:47], v[48:51], v[44:47], a[32:47]
	s_waitcnt vmcnt(13)
	ds_write_b128 v118, v[4:7] offset:0x8000
	v_mfma_f32_32x32x16_bf16 a[16:31], v[48:51], v[40:43], a[16:31]
	s_waitcnt vmcnt(12)
	ds_write_b128 v118, v[8:11] offset:0x9000
	v_mfma_f32_32x32x16_bf16 a[0:15], v[48:51], v[36:39], a[0:15]
	s_waitcnt vmcnt(11)
	ds_write_b128 v118, v[12:15] offset:0xa000
	s_waitcnt lgkmcnt(6)
	v_mfma_f32_32x32x16_bf16 a[80:95], v[124:127], v[80:83], a[80:95]
	s_waitcnt vmcnt(10)
	ds_write_b128 v118, v[16:19] offset:0xb000
	v_mfma_f32_32x32x16_bf16 a[48:63], v[124:127], v[112:115], a[48:63]
	s_waitcnt vmcnt(9)
	ds_write_b128 v118, v[20:23] offset:0xc000
	v_mfma_f32_32x32x16_bf16 a[64:79], v[124:127], v[120:123], a[64:79]
	s_waitcnt vmcnt(8)
	ds_write_b128 v118, v[24:27] offset:0xd000
	s_waitcnt lgkmcnt(8)
	v_mfma_f32_32x32x16_bf16 a[96:111], v[128:131], v[80:83], a[96:111]
	s_waitcnt vmcnt(7)
	ds_write_b128 v118, v[28:31] offset:0xe000
	v_mfma_f32_32x32x16_bf16 a[112:127], v[128:131], v[112:115], a[112:127]
	v_mfma_f32_32x32x16_bf16 a[128:143], v[128:131], v[120:123], a[128:143]
	s_waitcnt lgkmcnt(0)
	s_barrier
	ds_read_b128 v[36:39], v116 offset:0x8000
	ds_read_b128 v[40:43], v116 offset:0x8800
	ds_read_b128 v[44:47], v116 offset:0x9000
	ds_read_b128 v[48:51], v110 offset:0x8000
	v_mfma_f32_32x32x16_bf16 a[144:159], v[132:135], v[80:83], a[144:159]
	ds_read_b128 v[84:87], v110 offset:0x8800
	v_mfma_f32_32x32x16_bf16 a[160:175], v[132:135], v[112:115], a[160:175]
	ds_read_b128 v[88:91], v110 offset:0x9000
	v_add_u32_e32 v142, s6, v140
	v_add_u32_e32 v143, s6, v141
	global_load_dwordx4 v[4:7], v142, s[8:9]
	v_mfma_f32_32x32x16_bf16 a[176:191], v[132:135], v[120:123], a[176:191]
	ds_read_b128 v[92:95], v110 offset:0x9800
	global_load_dwordx4 v[8:11], v142, s[10:11]
	v_mfma_f32_32x32x16_bf16 a[32:47], v[136:139], v[80:83], a[32:47]
	global_load_dwordx4 v[12:15], v142, s[12:13]
	v_mfma_f32_32x32x16_bf16 a[16:31], v[136:139], v[112:115], a[16:31]
	global_load_dwordx4 v[16:19], v142, s[14:15]
	v_mfma_f32_32x32x16_bf16 a[0:15], v[136:139], v[120:123], a[0:15]
	global_load_dwordx4 v[20:23], v143, s[16:17]
	s_waitcnt lgkmcnt(3)
	v_mfma_f32_32x32x16_bf16 a[80:95], v[48:51], v[36:39], a[80:95]
	ds_read_b128 v[80:83], v117 offset:0x8000
	v_mfma_f32_32x32x16_bf16 a[48:63], v[48:51], v[40:43], a[48:63]
	global_load_dwordx4 v[24:27], v143, s[18:19]
	v_mfma_f32_32x32x16_bf16 a[64:79], v[48:51], v[44:47], a[64:79]
	ds_read_b128 v[112:115], v117 offset:0x8800
	s_waitcnt lgkmcnt(4)
	v_mfma_f32_32x32x16_bf16 a[96:111], v[84:87], v[36:39], a[96:111]
	global_load_dwordx4 v[28:31], v143, s[20:21]
	v_mfma_f32_32x32x16_bf16 a[112:127], v[84:87], v[40:43], a[112:127]
	ds_read_b128 v[128:131], v117 offset:0x9000
	v_mfma_f32_32x32x16_bf16 a[128:143], v[84:87], v[44:47], a[128:143]
	ds_read_b128 v[120:123], v111 offset:0x8000
	s_waitcnt lgkmcnt(5)
	v_mfma_f32_32x32x16_bf16 a[144:159], v[88:91], v[36:39], a[144:159]
	ds_read_b128 v[124:127], v111 offset:0x8800
	v_mfma_f32_32x32x16_bf16 a[160:175], v[88:91], v[40:43], a[160:175]
	ds_read_b128 v[136:139], v111 offset:0x9000
	v_mfma_f32_32x32x16_bf16 a[176:191], v[88:91], v[44:47], a[176:191]
	ds_read_b128 v[132:135], v111 offset:0x9800
	s_waitcnt lgkmcnt(7)
	v_mfma_f32_32x32x16_bf16 a[32:47], v[92:95], v[36:39], a[32:47]
	s_waitcnt vmcnt(13)
	ds_write_b128 v118, v[56:59] offset:0
	v_mfma_f32_32x32x16_bf16 a[16:31], v[92:95], v[40:43], a[16:31]
	s_waitcnt vmcnt(12)
	ds_write_b128 v118, v[52:55] offset:0x1000
	v_mfma_f32_32x32x16_bf16 a[0:15], v[92:95], v[44:47], a[0:15]
	s_waitcnt vmcnt(11)
	ds_write_b128 v118, v[64:67] offset:0x2000
	s_waitcnt lgkmcnt(6)
	v_mfma_f32_32x32x16_bf16 a[80:95], v[120:123], v[80:83], a[80:95]
	s_waitcnt vmcnt(10)
	ds_write_b128 v118, v[60:63] offset:0x3000
	v_mfma_f32_32x32x16_bf16 a[48:63], v[120:123], v[112:115], a[48:63]
	s_waitcnt vmcnt(9)
	ds_write_b128 v118, v[76:79] offset:0x4000
	v_mfma_f32_32x32x16_bf16 a[64:79], v[120:123], v[128:131], a[64:79]
	s_waitcnt vmcnt(8)
	ds_write_b128 v118, v[68:71] offset:0x5000
	s_waitcnt lgkmcnt(8)
	v_mfma_f32_32x32x16_bf16 a[96:111], v[124:127], v[80:83], a[96:111]
	s_waitcnt vmcnt(7)
	ds_write_b128 v118, v[72:75] offset:0x6000
	v_mfma_f32_32x32x16_bf16 a[112:127], v[124:127], v[112:115], a[112:127]
	v_mfma_f32_32x32x16_bf16 a[128:143], v[124:127], v[128:131], a[128:143]
	s_waitcnt lgkmcnt(0)
	s_cbranch_scc0 .Lrs0_last
	s_mov_b32 s4, s5
	s_add_i32 s5, s4, 64
	s_min_u32 s6, s5, 0x3e0
	s_lshl_b32 s78, s6, 1
	s_branch .Lrs0_top
.Lrs0_last:
	s_barrier
	s_mov_b32 s4, s5
	s_add_i32 s5, s4, 64
	s_min_u32 s6, s5, 0x3e0
	s_lshl_b32 s78, s6, 1
	ds_read_b128 v[44:47], v116 offset:0
	ds_read_b128 v[40:43], v116 offset:0x800
	ds_read_b128 v[36:39], v116 offset:0x1000
	ds_read_b128 v[92:95], v110 offset:0
	v_mfma_f32_32x32x16_bf16 a[144:159], v[136:139], v[80:83], a[144:159]
	ds_read_b128 v[88:91], v110 offset:0x800
	v_mfma_f32_32x32x16_bf16 a[160:175], v[136:139], v[112:115], a[160:175]
	ds_read_b128 v[84:87], v110 offset:0x1000
	v_mfma_f32_32x32x16_bf16 a[176:191], v[136:139], v[128:131], a[176:191]
	ds_read_b128 v[48:51], v110 offset:0x1800
	v_mfma_f32_32x32x16_bf16 a[32:47], v[132:135], v[80:83], a[32:47]
	v_mfma_f32_32x32x16_bf16 a[16:31], v[132:135], v[112:115], a[16:31]
	v_mfma_f32_32x32x16_bf16 a[0:15], v[132:135], v[128:131], a[0:15]
	s_waitcnt lgkmcnt(3)
	v_mfma_f32_32x32x16_bf16 a[80:95], v[92:95], v[44:47], a[80:95]
	ds_read_b128 v[80:83], v117 offset:0
	v_mfma_f32_32x32x16_bf16 a[48:63], v[92:95], v[40:43], a[48:63]
	v_mfma_f32_32x32x16_bf16 a[64:79], v[92:95], v[36:39], a[64:79]
	ds_read_b128 v[112:115], v117 offset:0x800
	s_waitcnt lgkmcnt(4)
	v_mfma_f32_32x32x16_bf16 a[96:111], v[88:91], v[44:47], a[96:111]
	v_mfma_f32_32x32x16_bf16 a[112:127], v[88:91], v[40:43], a[112:127]
	ds_read_b128 v[120:123], v117 offset:0x1000
	v_mfma_f32_32x32x16_bf16 a[128:143], v[88:91], v[36:39], a[128:143]
	ds_read_b128 v[124:127], v111 offset:0
	s_waitcnt lgkmcnt(5)
	v_mfma_f32_32x32x16_bf16 a[144:159], v[84:87], v[44:47], a[144:159]
	ds_read_b128 v[128:131], v111 offset:0x800
	s_min_u32 s4, s4, 0x380
	s_lshl_b32 s78, s4, 1
	v_mfma_f32_32x32x16_bf16 a[160:175], v[84:87], v[40:43], a[160:175]
	ds_read_b128 v[132:135], v111 offset:0x1000
	s_add_i32 s6, s78, 0xc0
	s_mov_b32 s7, s79
	v_mfma_f32_32x32x16_bf16 a[176:191], v[84:87], v[36:39], a[176:191]
	ds_read_b128 v[136:139], v111 offset:0x1800
	s_add_i32 s3, s3, 2
	s_cmp_lt_u32 s3, 30
	s_waitcnt lgkmcnt(7)
	v_mfma_f32_32x32x16_bf16 a[32:47], v[48:51], v[44:47], a[32:47]
	s_waitcnt vmcnt(6)
	ds_write_b128 v118, v[4:7] offset:0x8000
	v_mfma_f32_32x32x16_bf16 a[16:31], v[48:51], v[40:43], a[16:31]
	s_waitcnt vmcnt(5)
	ds_write_b128 v118, v[8:11] offset:0x9000
	v_mfma_f32_32x32x16_bf16 a[0:15], v[48:51], v[36:39], a[0:15]
	s_waitcnt vmcnt(4)
	ds_write_b128 v118, v[12:15] offset:0xa000
	s_waitcnt lgkmcnt(6)
	v_mfma_f32_32x32x16_bf16 a[80:95], v[124:127], v[80:83], a[80:95]
	s_waitcnt vmcnt(3)
	ds_write_b128 v118, v[16:19] offset:0xb000
	v_mfma_f32_32x32x16_bf16 a[48:63], v[124:127], v[112:115], a[48:63]
	s_waitcnt vmcnt(2)
	ds_write_b128 v118, v[20:23] offset:0xc000
	v_mfma_f32_32x32x16_bf16 a[64:79], v[124:127], v[120:123], a[64:79]
	s_waitcnt vmcnt(1)
	ds_write_b128 v118, v[24:27] offset:0xd000
	s_waitcnt lgkmcnt(8)
	v_mfma_f32_32x32x16_bf16 a[96:111], v[128:131], v[80:83], a[96:111]
	s_waitcnt vmcnt(0)
	ds_write_b128 v118, v[28:31] offset:0xe000
	v_mfma_f32_32x32x16_bf16 a[112:127], v[128:131], v[112:115], a[112:127]
	v_mfma_f32_32x32x16_bf16 a[128:143], v[128:131], v[120:123], a[128:143]
	s_waitcnt lgkmcnt(0)
	s_barrier
	ds_read_b128 v[36:39], v116 offset:0x8000
	ds_read_b128 v[40:43], v116 offset:0x8800
	ds_read_b128 v[44:47], v116 offset:0x9000
	ds_read_b128 v[48:51], v110 offset:0x8000
	v_mfma_f32_32x32x16_bf16 a[144:159], v[132:135], v[80:83], a[144:159]
	ds_read_b128 v[84:87], v110 offset:0x8800
	v_mfma_f32_32x32x16_bf16 a[160:175], v[132:135], v[112:115], a[160:175]
	ds_read_b128 v[88:91], v110 offset:0x9000
	v_mfma_f32_32x32x16_bf16 a[176:191], v[132:135], v[120:123], a[176:191]
	ds_read_b128 v[92:95], v110 offset:0x9800
	v_mfma_f32_32x32x16_bf16 a[32:47], v[136:139], v[80:83], a[32:47]
	v_mfma_f32_32x32x16_bf16 a[16:31], v[136:139], v[112:115], a[16:31]
	v_mfma_f32_32x32x16_bf16 a[0:15], v[136:139], v[120:123], a[0:15]
	s_waitcnt lgkmcnt(3)
	v_mfma_f32_32x32x16_bf16 a[80:95], v[48:51], v[36:39], a[80:95]
	ds_read_b128 v[80:83], v117 offset:0x8000
	v_mfma_f32_32x32x16_bf16 a[48:63], v[48:51], v[40:43], a[48:63]
	v_mfma_f32_32x32x16_bf16 a[64:79], v[48:51], v[44:47], a[64:79]
	ds_read_b128 v[112:115], v117 offset:0x8800
	s_waitcnt lgkmcnt(4)
	v_mfma_f32_32x32x16_bf16 a[96:111], v[84:87], v[36:39], a[96:111]
	v_mfma_f32_32x32x16_bf16 a[112:127], v[84:87], v[40:43], a[112:127]
	ds_read_b128 v[128:131], v117 offset:0x9000
	v_mfma_f32_32x32x16_bf16 a[128:143], v[84:87], v[44:47], a[128:143]
	ds_read_b128 v[120:123], v111 offset:0x8000
	s_waitcnt lgkmcnt(5)
	v_mfma_f32_32x32x16_bf16 a[144:159], v[88:91], v[36:39], a[144:159]
	ds_read_b128 v[124:127], v111 offset:0x8800
	v_mfma_f32_32x32x16_bf16 a[160:175], v[88:91], v[40:43], a[160:175]
	ds_read_b128 v[136:139], v111 offset:0x9000
	v_mfma_f32_32x32x16_bf16 a[176:191], v[88:91], v[44:47], a[176:191]
	ds_read_b128 v[132:135], v111 offset:0x9800
	s_waitcnt lgkmcnt(7)
	v_mfma_f32_32x32x16_bf16 a[32:47], v[92:95], v[36:39], a[32:47]
	v_mfma_f32_32x32x16_bf16 a[16:31], v[92:95], v[40:43], a[16:31]
	v_mfma_f32_32x32x16_bf16 a[0:15], v[92:95], v[44:47], a[0:15]
	s_waitcnt lgkmcnt(3)
	v_mfma_f32_32x32x16_bf16 a[80:95], v[120:123], v[80:83], a[80:95]
	v_mfma_f32_32x32x16_bf16 a[48:63], v[120:123], v[112:115], a[48:63]
	v_mfma_f32_32x32x16_bf16 a[64:79], v[120:123], v[128:131], a[64:79]
	s_waitcnt lgkmcnt(2)
	v_mfma_f32_32x32x16_bf16 a[96:111], v[124:127], v[80:83], a[96:111]
	v_mfma_f32_32x32x16_bf16 a[112:127], v[124:127], v[112:115], a[112:127]
	v_mfma_f32_32x32x16_bf16 a[128:143], v[124:127], v[128:131], a[128:143]
	s_waitcnt lgkmcnt(0)
	s_barrier
	v_mfma_f32_32x32x16_bf16 a[144:159], v[136:139], v[80:83], a[144:159]
	v_mfma_f32_32x32x16_bf16 a[160:175], v[136:139], v[112:115], a[160:175]
	v_mfma_f32_32x32x16_bf16 a[176:191], v[136:139], v[128:131], a[176:191]
	s_nop 7
	s_nop 3
	s_branch .LBB0_160

.LBB0_205:
	v_readfirstlane_b32 s10, v100
	v_readfirstlane_b32 s11, v101
	v_readfirstlane_b32 s12, v104
	v_readfirstlane_b32 s13, v105
	v_readfirstlane_b32 s14, v106
	v_readfirstlane_b32 s15, v107
	v_readfirstlane_b32 s16, v108
	v_readfirstlane_b32 s17, v109
	v_readfirstlane_b32 s18, v102
	v_readfirstlane_b32 s19, v103
	v_readfirstlane_b32 s20, v110
	v_readfirstlane_b32 s21, v111
	v_readfirstlane_b32 s22, v112
	v_readfirstlane_b32 s23, v113
	v_subrev_u32_e32 v140, s10, v100
	v_subrev_u32_e32 v141, s18, v102
	s_nop 4
	s_add_i32 s7, s6, 64
	s_min_u32 s8, s7, 0x3e0
	s_lshl_b32 s78, s8, 1
	ds_read_b128 v[52:55], v116 offset:0
	ds_read_b128 v[48:51], v116 offset:0x800
	ds_read_b128 v[44:47], v116 offset:0x1000
	ds_read_b128 v[96:99], v114 offset:0
	ds_read_b128 v[92:95], v114 offset:0x800
	ds_read_b128 v[88:91], v114 offset:0x1000
	v_add_u32_e32 v142, s78, v140
	v_add_u32_e32 v143, s78, v141
	global_load_dwordx4 v[64:67], v142, s[10:11]
	ds_read_b128 v[56:59], v114 offset:0x1800
	global_load_dwordx4 v[60:63], v142, s[12:13]
	global_load_dwordx4 v[72:75], v142, s[14:15]
	global_load_dwordx4 v[68:71], v142, s[16:17]
	global_load_dwordx4 v[84:87], v143, s[18:19]
	s_waitcnt lgkmcnt(3)
	v_mfma_f32_32x32x16_bf16 a[48:63], v[96:99], v[52:55], 0
	ds_read_b128 v[36:39], v117 offset:0
	v_mfma_f32_32x32x16_bf16 a[64:79], v[96:99], v[48:51], 0
	global_load_dwordx4 v[76:79], v143, s[20:21]
	v_mfma_f32_32x32x16_bf16 a[80:95], v[96:99], v[44:47], 0
	ds_read_b128 v[40:43], v117 offset:0x800
	s_waitcnt lgkmcnt(4)
	v_mfma_f32_32x32x16_bf16 a[96:111], v[92:95], v[52:55], 0
	global_load_dwordx4 v[80:83], v143, s[22:23]
	v_mfma_f32_32x32x16_bf16 a[112:127], v[92:95], v[48:51], 0
	ds_read_b128 v[120:123], v117 offset:0x1000
	v_mfma_f32_32x32x16_bf16 a[128:143], v[92:95], v[44:47], 0
	ds_read_b128 v[124:127], v115 offset:0
	s_waitcnt lgkmcnt(5)
	v_mfma_f32_32x32x16_bf16 a[144:159], v[88:91], v[52:55], 0
	ds_read_b128 v[128:131], v115 offset:0x800
	s_min_u32 s6, s6, 0x380
	s_lshl_b32 s78, s6, 1
	v_mfma_f32_32x32x16_bf16 a[160:175], v[88:91], v[48:51], 0
	ds_read_b128 v[132:135], v115 offset:0x1000
	s_add_i32 s8, s78, 0xc0
	s_mov_b32 s9, s79
	v_mfma_f32_32x32x16_bf16 a[176:191], v[88:91], v[44:47], 0
	ds_read_b128 v[136:139], v115 offset:0x1800
	s_add_i32 s5, s5, 2
	s_cmp_lt_u32 s5, 30
	s_waitcnt lgkmcnt(7)
	v_mfma_f32_32x32x16_bf16 a[32:47], v[56:59], v[52:55], 0
	s_waitcnt vmcnt(13)
	ds_write_b128 v118, v[4:7] offset:0x8000
	v_mfma_f32_32x32x16_bf16 a[16:31], v[56:59], v[48:51], 0
	s_waitcnt vmcnt(12)
	ds_write_b128 v118, v[8:11] offset:0x9000
	v_mfma_f32_32x32x16_bf16 a[0:15], v[56:59], v[44:47], 0
	s_waitcnt vmcnt(11)
	ds_write_b128 v118, v[12:15] offset:0xa000
	s_waitcnt lgkmcnt(6)
	v_mfma_f32_32x32x16_bf16 a[48:63], v[124:127], v[36:39], a[48:63]
	s_waitcnt vmcnt(10)
	ds_write_b128 v118, v[16:19] offset:0xb000
	v_mfma_f32_32x32x16_bf16 a[64:79], v[124:127], v[40:43], a[64:79]
	s_waitcnt vmcnt(9)
	ds_write_b128 v118, v[20:23] offset:0xc000
	v_mfma_f32_32x32x16_bf16 a[80:95], v[124:127], v[120:123], a[80:95]
	s_waitcnt vmcnt(8)
	ds_write_b128 v118, v[24:27] offset:0xd000
	s_waitcnt lgkmcnt(8)
	v_mfma_f32_32x32x16_bf16 a[96:111], v[128:131], v[36:39], a[96:111]
	s_waitcnt vmcnt(7)
	ds_write_b128 v118, v[28:31] offset:0xe000
	v_mfma_f32_32x32x16_bf16 a[112:127], v[128:131], v[40:43], a[112:127]
	v_mfma_f32_32x32x16_bf16 a[128:143], v[128:131], v[120:123], a[128:143]
	s_waitcnt lgkmcnt(0)
	s_barrier
	ds_read_b128 v[44:47], v116 offset:0x8000
	ds_read_b128 v[48:51], v116 offset:0x8800
	ds_read_b128 v[52:55], v116 offset:0x9000
	ds_read_b128 v[56:59], v114 offset:0x8000
	v_mfma_f32_32x32x16_bf16 a[144:159], v[132:135], v[36:39], a[144:159]
	ds_read_b128 v[88:91], v114 offset:0x8800
	v_mfma_f32_32x32x16_bf16 a[160:175], v[132:135], v[40:43], a[160:175]
	ds_read_b128 v[92:95], v114 offset:0x9000
	v_add_u32_e32 v142, s8, v140
	v_add_u32_e32 v143, s8, v141
	global_load_dwordx4 v[4:7], v142, s[10:11]
	v_mfma_f32_32x32x16_bf16 a[176:191], v[132:135], v[120:123], a[176:191]
	ds_read_b128 v[96:99], v114 offset:0x9800
	global_load_dwordx4 v[8:11], v142, s[12:13]
	v_mfma_f32_32x32x16_bf16 a[32:47], v[136:139], v[36:39], a[32:47]
	global_load_dwordx4 v[12:15], v142, s[14:15]
	v_mfma_f32_32x32x16_bf16 a[16:31], v[136:139], v[40:43], a[16:31]
	global_load_dwordx4 v[16:19], v142, s[16:17]
	v_mfma_f32_32x32x16_bf16 a[0:15], v[136:139], v[120:123], a[0:15]
	global_load_dwordx4 v[20:23], v143, s[18:19]
	s_waitcnt lgkmcnt(3)
	v_mfma_f32_32x32x16_bf16 a[48:63], v[56:59], v[44:47], a[48:63]
	ds_read_b128 v[40:43], v117 offset:0x8000
	v_mfma_f32_32x32x16_bf16 a[64:79], v[56:59], v[48:51], a[64:79]
	global_load_dwordx4 v[24:27], v143, s[20:21]
	v_mfma_f32_32x32x16_bf16 a[80:95], v[56:59], v[52:55], a[80:95]
	ds_read_b128 v[36:39], v117 offset:0x8800
	s_waitcnt lgkmcnt(4)
	v_mfma_f32_32x32x16_bf16 a[96:111], v[88:91], v[44:47], a[96:111]
	global_load_dwordx4 v[28:31], v143, s[22:23]
	v_mfma_f32_32x32x16_bf16 a[112:127], v[88:91], v[48:51], a[112:127]
	ds_read_b128 v[194:197], v117 offset:0x9000
	v_mfma_f32_32x32x16_bf16 a[128:143], v[88:91], v[52:55], a[128:143]
	ds_read_b128 v[120:123], v115 offset:0x8000
	s_waitcnt lgkmcnt(5)
	v_mfma_f32_32x32x16_bf16 a[144:159], v[92:95], v[44:47], a[144:159]
	ds_read_b128 v[124:127], v115 offset:0x8800
	v_mfma_f32_32x32x16_bf16 a[160:175], v[92:95], v[48:51], a[160:175]
	ds_read_b128 v[128:131], v115 offset:0x9000
	v_mfma_f32_32x32x16_bf16 a[176:191], v[92:95], v[52:55], a[176:191]
	ds_read_b128 v[198:201], v115 offset:0x9800
	s_waitcnt lgkmcnt(7)
	v_mfma_f32_32x32x16_bf16 a[32:47], v[96:99], v[44:47], a[32:47]
	s_waitcnt vmcnt(13)
	ds_write_b128 v118, v[64:67] offset:0
	v_mfma_f32_32x32x16_bf16 a[16:31], v[96:99], v[48:51], a[16:31]
	s_waitcnt vmcnt(12)
	ds_write_b128 v118, v[60:63] offset:0x1000
	v_mfma_f32_32x32x16_bf16 a[0:15], v[96:99], v[52:55], a[0:15]
	s_waitcnt vmcnt(11)
	ds_write_b128 v118, v[72:75] offset:0x2000
	s_waitcnt lgkmcnt(6)
	v_mfma_f32_32x32x16_bf16 a[48:63], v[120:123], v[40:43], a[48:63]
	s_waitcnt vmcnt(10)
	ds_write_b128 v118, v[68:71] offset:0x3000
	v_mfma_f32_32x32x16_bf16 a[64:79], v[120:123], v[36:39], a[64:79]
	s_waitcnt vmcnt(9)
	ds_write_b128 v118, v[84:87] offset:0x4000
	v_mfma_f32_32x32x16_bf16 a[80:95], v[120:123], v[194:197], a[80:95]
	s_waitcnt vmcnt(8)
	ds_write_b128 v118, v[76:79] offset:0x5000
	s_waitcnt lgkmcnt(8)
	v_mfma_f32_32x32x16_bf16 a[96:111], v[124:127], v[40:43], a[96:111]
	s_waitcnt vmcnt(7)
	ds_write_b128 v118, v[80:83] offset:0x6000
	v_mfma_f32_32x32x16_bf16 a[112:127], v[124:127], v[36:39], a[112:127]
	v_mfma_f32_32x32x16_bf16 a[128:143], v[124:127], v[194:197], a[128:143]
	s_waitcnt lgkmcnt(0)
	s_mov_b32 s6, s7
	s_add_i32 s7, s6, 64
	s_min_u32 s8, s7, 0x3e0
	s_lshl_b32 s78, s8, 1
.Lrs3_top:
	s_barrier
	ds_read_b128 v[52:55], v116 offset:0
	ds_read_b128 v[48:51], v116 offset:0x800
	ds_read_b128 v[44:47], v116 offset:0x1000
	ds_read_b128 v[96:99], v114 offset:0
	v_mfma_f32_32x32x16_bf16 a[144:159], v[128:131], v[40:43], a[144:159]
	ds_read_b128 v[92:95], v114 offset:0x800
	v_mfma_f32_32x32x16_bf16 a[160:175], v[128:131], v[36:39], a[160:175]
	ds_read_b128 v[88:91], v114 offset:0x1000
	v_add_u32_e32 v142, s78, v140
	v_add_u32_e32 v143, s78, v141
	global_load_dwordx4 v[64:67], v142, s[10:11]
	v_mfma_f32_32x32x16_bf16 a[176:191], v[128:131], v[194:197], a[176:191]
	ds_read_b128 v[56:59], v114 offset:0x1800
	global_load_dwordx4 v[60:63], v142, s[12:13]
	v_mfma_f32_32x32x16_bf16 a[32:47], v[198:201], v[40:43], a[32:47]
	global_load_dwordx4 v[72:75], v142, s[14:15]
	v_mfma_f32_32x32x16_bf16 a[16:31], v[198:201], v[36:39], a[16:31]
	global_load_dwordx4 v[68:71], v142, s[16:17]
	v_mfma_f32_32x32x16_bf16 a[0:15], v[198:201], v[194:197], a[0:15]
	global_load_dwordx4 v[84:87], v143, s[18:19]
	s_waitcnt lgkmcnt(3)
	v_mfma_f32_32x32x16_bf16 a[48:63], v[96:99], v[52:55], a[48:63]
	ds_read_b128 v[36:39], v117 offset:0
	v_mfma_f32_32x32x16_bf16 a[64:79], v[96:99], v[48:51], a[64:79]
	global_load_dwordx4 v[76:79], v143, s[20:21]
	v_mfma_f32_32x32x16_bf16 a[80:95], v[96:99], v[44:47], a[80:95]
	ds_read_b128 v[40:43], v117 offset:0x800
	s_waitcnt lgkmcnt(4)
	v_mfma_f32_32x32x16_bf16 a[96:111], v[92:95], v[52:55], a[96:111]
	global_load_dwordx4 v[80:83], v143, s[22:23]
	v_mfma_f32_32x32x16_bf16 a[112:127], v[92:95], v[48:51], a[112:127]
	ds_read_b128 v[120:123], v117 offset:0x1000
	v_mfma_f32_32x32x16_bf16 a[128:143], v[92:95], v[44:47], a[128:143]
	ds_read_b128 v[124:127], v115 offset:0
	s_waitcnt lgkmcnt(5)
	v_mfma_f32_32x32x16_bf16 a[144:159], v[88:91], v[52:55], a[144:159]
	ds_read_b128 v[128:131], v115 offset:0x800
	s_min_u32 s6, s6, 0x380
	s_lshl_b32 s78, s6, 1
	v_mfma_f32_32x32x16_bf16 a[160:175], v[88:91], v[48:51], a[160:175]
	ds_read_b128 v[132:135], v115 offset:0x1000
	s_add_i32 s8, s78, 0xc0
	s_mov_b32 s9, s79
	v_mfma_f32_32x32x16_bf16 a[176:191], v[88:91], v[44:47], a[176:191]
	ds_read_b128 v[136:139], v115 offset:0x1800
	s_add_i32 s5, s5, 2
	s_cmp_lt_u32 s5, 28
	s_waitcnt lgkmcnt(7)
	v_mfma_f32_32x32x16_bf16 a[32:47], v[56:59], v[52:55], a[32:47]
	s_waitcnt vmcnt(13)
	ds_write_b128 v118, v[4:7] offset:0x8000
	v_mfma_f32_32x32x16_bf16 a[16:31], v[56:59], v[48:51], a[16:31]
	s_waitcnt vmcnt(12)
	ds_write_b128 v118, v[8:11] offset:0x9000
	v_mfma_f32_32x32x16_bf16 a[0:15], v[56:59], v[44:47], a[0:15]
	s_waitcnt vmcnt(11)
	ds_write_b128 v118, v[12:15] offset:0xa000
	s_waitcnt lgkmcnt(6)
	v_mfma_f32_32x32x16_bf16 a[48:63], v[124:127], v[36:39], a[48:63]
	s_waitcnt vmcnt(10)
	ds_write_b128 v118, v[16:19] offset:0xb000
	v_mfma_f32_32x32x16_bf16 a[64:79], v[124:127], v[40:43], a[64:79]
	s_waitcnt vmcnt(9)
	ds_write_b128 v118, v[20:23] offset:0xc000
	v_mfma_f32_32x32x16_bf16 a[80:95], v[124:127], v[120:123], a[80:95]
	s_waitcnt vmcnt(8)
	ds_write_b128 v118, v[24:27] offset:0xd000
	s_waitcnt lgkmcnt(8)
	v_mfma_f32_32x32x16_bf16 a[96:111], v[128:131], v[36:39], a[96:111]
	s_waitcnt vmcnt(7)
	ds_write_b128 v118, v[28:31] offset:0xe000
	v_mfma_f32_32x32x16_bf16 a[112:127], v[128:131], v[40:43], a[112:127]
	v_mfma_f32_32x32x16_bf16 a[128:143], v[128:131], v[120:123], a[128:143]
	s_waitcnt lgkmcnt(0)
	s_barrier
	ds_read_b128 v[44:47], v116 offset:0x8000
	ds_read_b128 v[48:51], v116 offset:0x8800
	ds_read_b128 v[52:55], v116 offset:0x9000
	ds_read_b128 v[56:59], v114 offset:0x8000
	v_mfma_f32_32x32x16_bf16 a[144:159], v[132:135], v[36:39], a[144:159]
	ds_read_b128 v[88:91], v114 offset:0x8800
	v_mfma_f32_32x32x16_bf16 a[160:175], v[132:135], v[40:43], a[160:175]
	ds_read_b128 v[92:95], v114 offset:0x9000
	v_add_u32_e32 v142, s8, v140
	v_add_u32_e32 v143, s8, v141
	global_load_dwordx4 v[4:7], v142, s[10:11]
	v_mfma_f32_32x32x16_bf16 a[176:191], v[132:135], v[120:123], a[176:191]
	ds_read_b128 v[96:99], v114 offset:0x9800
	global_load_dwordx4 v[8:11], v142, s[12:13]
	v_mfma_f32_32x32x16_bf16 a[32:47], v[136:139], v[36:39], a[32:47]
	global_load_dwordx4 v[12:15], v142, s[14:15]
	v_mfma_f32_32x32x16_bf16 a[16:31], v[136:139], v[40:43], a[16:31]
	global_load_dwordx4 v[16:19], v142, s[16:17]
	v_mfma_f32_32x32x16_bf16 a[0:15], v[136:139], v[120:123], a[0:15]
	global_load_dwordx4 v[20:23], v143, s[18:19]
	s_waitcnt lgkmcnt(3)
	v_mfma_f32_32x32x16_bf16 a[48:63], v[56:59], v[44:47], a[48:63]
	ds_read_b128 v[40:43], v117 offset:0x8000
	v_mfma_f32_32x32x16_bf16 a[64:79], v[56:59], v[48:51], a[64:79]
	global_load_dwordx4 v[24:27], v143, s[20:21]
	v_mfma_f32_32x32x16_bf16 a[80:95], v[56:59], v[52:55], a[80:95]
	ds_read_b128 v[36:39], v117 offset:0x8800
	s_waitcnt lgkmcnt(4)
	v_mfma_f32_32x32x16_bf16 a[96:111], v[88:91], v[44:47], a[96:111]
	global_load_dwordx4 v[28:31], v143, s[22:23]
	v_mfma_f32_32x32x16_bf16 a[112:127], v[88:91], v[48:51], a[112:127]
	ds_read_b128 v[194:197], v117 offset:0x9000
	v_mfma_f32_32x32x16_bf16 a[128:143], v[88:91], v[52:55], a[128:143]
	ds_read_b128 v[120:123], v115 offset:0x8000
	s_waitcnt lgkmcnt(5)
	v_mfma_f32_32x32x16_bf16 a[144:159], v[92:95], v[44:47], a[144:159]
	ds_read_b128 v[124:127], v115 offset:0x8800
	v_mfma_f32_32x32x16_bf16 a[160:175], v[92:95], v[48:51], a[160:175]
	ds_read_b128 v[128:131], v115 offset:0x9000
	v_mfma_f32_32x32x16_bf16 a[176:191], v[92:95], v[52:55], a[176:191]
	ds_read_b128 v[198:201], v115 offset:0x9800
	s_waitcnt lgkmcnt(7)
	v_mfma_f32_32x32x16_bf16 a[32:47], v[96:99], v[44:47], a[32:47]
	s_waitcnt vmcnt(13)
	ds_write_b128 v118, v[64:67] offset:0
	v_mfma_f32_32x32x16_bf16 a[16:31], v[96:99], v[48:51], a[16:31]
	s_waitcnt vmcnt(12)
	ds_write_b128 v118, v[60:63] offset:0x1000
	v_mfma_f32_32x32x16_bf16 a[0:15], v[96:99], v[52:55], a[0:15]
	s_waitcnt vmcnt(11)
	ds_write_b128 v118, v[72:75] offset:0x2000
	s_waitcnt lgkmcnt(6)
	v_mfma_f32_32x32x16_bf16 a[48:63], v[120:123], v[40:43], a[48:63]
	s_waitcnt vmcnt(10)
	ds_write_b128 v118, v[68:71] offset:0x3000
	v_mfma_f32_32x32x16_bf16 a[64:79], v[120:123], v[36:39], a[64:79]
	s_waitcnt vmcnt(9)
	ds_write_b128 v118, v[84:87] offset:0x4000
	v_mfma_f32_32x32x16_bf16 a[80:95], v[120:123], v[194:197], a[80:95]
	s_waitcnt vmcnt(8)
	ds_write_b128 v118, v[76:79] offset:0x5000
	s_waitcnt lgkmcnt(8)
	v_mfma_f32_32x32x16_bf16 a[96:111], v[124:127], v[40:43], a[96:111]
	s_waitcnt vmcnt(7)
	ds_write_b128 v118, v[80:83] offset:0x6000
	v_mfma_f32_32x32x16_bf16 a[112:127], v[124:127], v[36:39], a[112:127]
	v_mfma_f32_32x32x16_bf16 a[128:143], v[124:127], v[194:197], a[128:143]
	s_waitcnt lgkmcnt(0)
	s_cbranch_scc0 .Lrs3_last
	s_mov_b32 s6, s7
	s_add_i32 s7, s6, 64
	s_min_u32 s8, s7, 0x3e0
	s_lshl_b32 s78, s8, 1
	s_branch .Lrs3_top
.Lrs3_last:
	s_barrier
	s_mov_b32 s6, s7
	s_add_i32 s7, s6, 64
	s_min_u32 s8, s7, 0x3e0
	s_lshl_b32 s78, s8, 1
	ds_read_b128 v[52:55], v116 offset:0
	ds_read_b128 v[48:51], v116 offset:0x800
	ds_read_b128 v[44:47], v116 offset:0x1000
	ds_read_b128 v[96:99], v114 offset:0
	v_mfma_f32_32x32x16_bf16 a[144:159], v[128:131], v[40:43], a[144:159]
	ds_read_b128 v[92:95], v114 offset:0x800
	v_mfma_f32_32x32x16_bf16 a[160:175], v[128:131], v[36:39], a[160:175]
	ds_read_b128 v[88:91], v114 offset:0x1000
	v_mfma_f32_32x32x16_bf16 a[176:191], v[128:131], v[194:197], a[176:191]
	ds_read_b128 v[56:59], v114 offset:0x1800
	v_mfma_f32_32x32x16_bf16 a[32:47], v[198:201], v[40:43], a[32:47]
	v_mfma_f32_32x32x16_bf16 a[16:31], v[198:201], v[36:39], a[16:31]
	v_mfma_f32_32x32x16_bf16 a[0:15], v[198:201], v[194:197], a[0:15]
	s_waitcnt lgkmcnt(3)
	v_mfma_f32_32x32x16_bf16 a[48:63], v[96:99], v[52:55], a[48:63]
	ds_read_b128 v[36:39], v117 offset:0
	v_mfma_f32_32x32x16_bf16 a[64:79], v[96:99], v[48:51], a[64:79]
	v_mfma_f32_32x32x16_bf16 a[80:95], v[96:99], v[44:47], a[80:95]
	ds_read_b128 v[40:43], v117 offset:0x800
	s_waitcnt lgkmcnt(4)
	v_mfma_f32_32x32x16_bf16 a[96:111], v[92:95], v[52:55], a[96:111]
	v_mfma_f32_32x32x16_bf16 a[112:127], v[92:95], v[48:51], a[112:127]
	ds_read_b128 v[120:123], v117 offset:0x1000
	v_mfma_f32_32x32x16_bf16 a[128:143], v[92:95], v[44:47], a[128:143]
	ds_read_b128 v[124:127], v115 offset:0
	s_waitcnt lgkmcnt(5)
	v_mfma_f32_32x32x16_bf16 a[144:159], v[88:91], v[52:55], a[144:159]
	ds_read_b128 v[128:131], v115 offset:0x800
	s_min_u32 s6, s6, 0x380
	s_lshl_b32 s78, s6, 1
	v_mfma_f32_32x32x16_bf16 a[160:175], v[88:91], v[48:51], a[160:175]
	ds_read_b128 v[132:135], v115 offset:0x1000
	s_add_i32 s8, s78, 0xc0
	s_mov_b32 s9, s79
	v_mfma_f32_32x32x16_bf16 a[176:191], v[88:91], v[44:47], a[176:191]
	ds_read_b128 v[136:139], v115 offset:0x1800
	s_add_i32 s5, s5, 2
	s_cmp_lt_u32 s5, 30
	s_waitcnt lgkmcnt(7)
	v_mfma_f32_32x32x16_bf16 a[32:47], v[56:59], v[52:55], a[32:47]
	s_waitcnt vmcnt(6)
	ds_write_b128 v118, v[4:7] offset:0x8000
	v_mfma_f32_32x32x16_bf16 a[16:31], v[56:59], v[48:51], a[16:31]
	s_waitcnt vmcnt(5)
	ds_write_b128 v118, v[8:11] offset:0x9000
	v_mfma_f32_32x32x16_bf16 a[0:15], v[56:59], v[44:47], a[0:15]
	s_waitcnt vmcnt(4)
	ds_write_b128 v118, v[12:15] offset:0xa000
	s_waitcnt lgkmcnt(6)
	v_mfma_f32_32x32x16_bf16 a[48:63], v[124:127], v[36:39], a[48:63]
	s_waitcnt vmcnt(3)
	ds_write_b128 v118, v[16:19] offset:0xb000
	v_mfma_f32_32x32x16_bf16 a[64:79], v[124:127], v[40:43], a[64:79]
	s_waitcnt vmcnt(2)
	ds_write_b128 v118, v[20:23] offset:0xc000
	v_mfma_f32_32x32x16_bf16 a[80:95], v[124:127], v[120:123], a[80:95]
	s_waitcnt vmcnt(1)
	ds_write_b128 v118, v[24:27] offset:0xd000
	s_waitcnt lgkmcnt(8)
	v_mfma_f32_32x32x16_bf16 a[96:111], v[128:131], v[36:39], a[96:111]
	s_waitcnt vmcnt(0)
	ds_write_b128 v118, v[28:31] offset:0xe000
	v_mfma_f32_32x32x16_bf16 a[112:127], v[128:131], v[40:43], a[112:127]
	v_mfma_f32_32x32x16_bf16 a[128:143], v[128:131], v[120:123], a[128:143]
	s_waitcnt lgkmcnt(0)
	s_barrier
	ds_read_b128 v[44:47], v116 offset:0x8000
	ds_read_b128 v[48:51], v116 offset:0x8800
	ds_read_b128 v[52:55], v116 offset:0x9000
	ds_read_b128 v[56:59], v114 offset:0x8000
	v_mfma_f32_32x32x16_bf16 a[144:159], v[132:135], v[36:39], a[144:159]
	ds_read_b128 v[88:91], v114 offset:0x8800
	v_mfma_f32_32x32x16_bf16 a[160:175], v[132:135], v[40:43], a[160:175]
	ds_read_b128 v[92:95], v114 offset:0x9000
	v_mfma_f32_32x32x16_bf16 a[176:191], v[132:135], v[120:123], a[176:191]
	ds_read_b128 v[96:99], v114 offset:0x9800
	v_mfma_f32_32x32x16_bf16 a[32:47], v[136:139], v[36:39], a[32:47]
	v_mfma_f32_32x32x16_bf16 a[16:31], v[136:139], v[40:43], a[16:31]
	v_mfma_f32_32x32x16_bf16 a[0:15], v[136:139], v[120:123], a[0:15]
	s_waitcnt lgkmcnt(3)
	v_mfma_f32_32x32x16_bf16 a[48:63], v[56:59], v[44:47], a[48:63]
	ds_read_b128 v[40:43], v117 offset:0x8000
	v_mfma_f32_32x32x16_bf16 a[64:79], v[56:59], v[48:51], a[64:79]
	v_mfma_f32_32x32x16_bf16 a[80:95], v[56:59], v[52:55], a[80:95]
	ds_read_b128 v[36:39], v117 offset:0x8800
	s_waitcnt lgkmcnt(4)
	v_mfma_f32_32x32x16_bf16 a[96:111], v[88:91], v[44:47], a[96:111]
	v_mfma_f32_32x32x16_bf16 a[112:127], v[88:91], v[48:51], a[112:127]
	ds_read_b128 v[194:197], v117 offset:0x9000
	v_mfma_f32_32x32x16_bf16 a[128:143], v[88:91], v[52:55], a[128:143]
	ds_read_b128 v[120:123], v115 offset:0x8000
	s_waitcnt lgkmcnt(5)
	v_mfma_f32_32x32x16_bf16 a[144:159], v[92:95], v[44:47], a[144:159]
	ds_read_b128 v[124:127], v115 offset:0x8800
	v_mfma_f32_32x32x16_bf16 a[160:175], v[92:95], v[48:51], a[160:175]
	ds_read_b128 v[128:131], v115 offset:0x9000
	v_mfma_f32_32x32x16_bf16 a[176:191], v[92:95], v[52:55], a[176:191]
	ds_read_b128 v[198:201], v115 offset:0x9800
	s_waitcnt lgkmcnt(7)
	v_mfma_f32_32x32x16_bf16 a[32:47], v[96:99], v[44:47], a[32:47]
	v_mfma_f32_32x32x16_bf16 a[16:31], v[96:99], v[48:51], a[16:31]
	v_mfma_f32_32x32x16_bf16 a[0:15], v[96:99], v[52:55], a[0:15]
	s_waitcnt lgkmcnt(3)
	v_mfma_f32_32x32x16_bf16 a[48:63], v[120:123], v[40:43], a[48:63]
	v_mfma_f32_32x32x16_bf16 a[64:79], v[120:123], v[36:39], a[64:79]
	v_mfma_f32_32x32x16_bf16 a[80:95], v[120:123], v[194:197], a[80:95]
	s_waitcnt lgkmcnt(2)
	v_mfma_f32_32x32x16_bf16 a[96:111], v[124:127], v[40:43], a[96:111]
	v_mfma_f32_32x32x16_bf16 a[112:127], v[124:127], v[36:39], a[112:127]
	v_mfma_f32_32x32x16_bf16 a[128:143], v[124:127], v[194:197], a[128:143]
	s_waitcnt lgkmcnt(0)
	s_barrier
	v_mfma_f32_32x32x16_bf16 a[144:159], v[128:131], v[40:43], a[144:159]
	v_mfma_f32_32x32x16_bf16 a[160:175], v[128:131], v[36:39], a[160:175]
	v_mfma_f32_32x32x16_bf16 a[176:191], v[128:131], v[194:197], a[176:191]
	s_nop 7
	s_nop 3
	s_branch .LBB0_203

.LBB0_224:
	v_readfirstlane_b32 s8, v68
	v_readfirstlane_b32 s9, v69
	v_readfirstlane_b32 s10, v72
	v_readfirstlane_b32 s11, v73
	v_readfirstlane_b32 s12, v74
	v_readfirstlane_b32 s13, v75
	v_readfirstlane_b32 s14, v76
	v_readfirstlane_b32 s15, v77
	v_readfirstlane_b32 s16, v70
	v_readfirstlane_b32 s17, v71
	v_readfirstlane_b32 s18, v78
	v_readfirstlane_b32 s19, v79
	v_subrev_u32_e32 v144, s8, v68
	v_subrev_u32_e32 v145, s16, v70
	s_nop 4
	s_add_i32 s5, s4, 64
	s_min_u32 s6, s5, 0x3e0
	s_lshl_b32 s78, s6, 1
	ds_read_b128 v[48:51], v82 offset:0
	ds_read_b128 v[44:47], v82 offset:0x800
	ds_read_b128 v[64:67], v80 offset:0
	ds_read_b128 v[60:63], v80 offset:0x800
	ds_read_b128 v[56:59], v80 offset:0x1000
	v_add_u32_e32 v146, s78, v144
	v_add_u32_e32 v147, s78, v145
	global_load_dwordx4 v[106:109], v146, s[8:9]
	ds_read_b128 v[52:55], v80 offset:0x1800
	global_load_dwordx4 v[110:113], v146, s[10:11]
	global_load_dwordx4 v[114:117], v146, s[12:13]
	s_waitcnt lgkmcnt(3)
	v_mfma_f32_32x32x16_bf16 a[32:47], v[64:67], v[48:51], 0
	ds_read_b128 v[40:43], v83 offset:0
	v_mfma_f32_32x32x16_bf16 a[48:63], v[64:67], v[44:47], 0
	global_load_dwordx4 v[118:121], v146, s[14:15]
	s_waitcnt lgkmcnt(3)
	v_mfma_f32_32x32x16_bf16 a[64:79], v[60:63], v[48:51], 0
	ds_read_b128 v[86:89], v83 offset:0x800
	v_mfma_f32_32x32x16_bf16 a[80:95], v[60:63], v[44:47], 0
	global_load_dwordx4 v[122:125], v147, s[16:17]
	s_waitcnt lgkmcnt(3)
	v_mfma_f32_32x32x16_bf16 a[96:111], v[56:59], v[48:51], 0
	ds_read_b128 v[90:93], v81 offset:0
	v_mfma_f32_32x32x16_bf16 a[112:127], v[56:59], v[44:47], 0
	global_load_dwordx4 v[140:143], v147, s[18:19]
	s_waitcnt vmcnt(11)
	ds_write_b128 v84, v[4:7] offset:0x8000
	s_waitcnt lgkmcnt(4)
	v_mfma_f32_32x32x16_bf16 a[16:31], v[52:55], v[48:51], 0
	ds_read_b128 v[94:97], v81 offset:0x800
	s_min_u32 s4, s4, 0x380
	s_lshl_b32 s78, s4, 1
	s_waitcnt vmcnt(10)
	ds_write_b128 v84, v[8:11] offset:0x9000
	v_mfma_f32_32x32x16_bf16 a[0:15], v[52:55], v[44:47], 0
	ds_read_b128 v[98:101], v81 offset:0x1000
	s_add_i32 s6, s78, 0xc0
	s_mov_b32 s7, s79
	s_waitcnt vmcnt(9)
	ds_write_b128 v84, v[12:15] offset:0xa000
	s_waitcnt lgkmcnt(5)
	v_mfma_f32_32x32x16_bf16 a[32:47], v[90:93], v[40:43], a[32:47]
	ds_read_b128 v[102:105], v81 offset:0x1800
	s_add_i32 s3, s3, 2
	s_cmp_lt_u32 s3, 30
	s_waitcnt vmcnt(8)
	ds_write_b128 v84, v[16:19] offset:0xb000
	v_mfma_f32_32x32x16_bf16 a[48:63], v[90:93], v[86:89], a[48:63]
	s_waitcnt vmcnt(7)
	ds_write_b128 v84, v[20:23] offset:0xc000
	s_waitcnt lgkmcnt(6)
	v_mfma_f32_32x32x16_bf16 a[64:79], v[94:97], v[40:43], a[64:79]
	s_waitcnt vmcnt(6)
	ds_write_b128 v84, v[24:27] offset:0xd000
	v_mfma_f32_32x32x16_bf16 a[80:95], v[94:97], v[86:89], a[80:95]
	s_waitcnt lgkmcnt(0)
	s_barrier
	ds_read_b128 v[44:47], v82 offset:0x8000
	ds_read_b128 v[48:51], v82 offset:0x8800
	ds_read_b128 v[52:55], v80 offset:0x8000
	v_mfma_f32_32x32x16_bf16 a[96:111], v[98:101], v[40:43], a[96:111]
	ds_read_b128 v[56:59], v80 offset:0x8800
	v_mfma_f32_32x32x16_bf16 a[112:127], v[98:101], v[86:89], a[112:127]
	ds_read_b128 v[60:63], v80 offset:0x9000
	v_add_u32_e32 v146, s6, v144
	v_add_u32_e32 v147, s6, v145
	global_load_dwordx4 v[4:7], v146, s[8:9]
	v_mfma_f32_32x32x16_bf16 a[16:31], v[102:105], v[40:43], a[16:31]
	ds_read_b128 v[64:67], v80 offset:0x9800
	global_load_dwordx4 v[8:11], v146, s[10:11]
	v_mfma_f32_32x32x16_bf16 a[0:15], v[102:105], v[86:89], a[0:15]
	global_load_dwordx4 v[12:15], v146, s[12:13]
	s_waitcnt lgkmcnt(3)
	v_mfma_f32_32x32x16_bf16 a[32:47], v[52:55], v[44:47], a[32:47]
	ds_read_b128 v[40:43], v83 offset:0x8000
	v_mfma_f32_32x32x16_bf16 a[48:63], v[52:55], v[48:51], a[48:63]
	global_load_dwordx4 v[16:19], v146, s[14:15]
	s_waitcnt lgkmcnt(3)
	v_mfma_f32_32x32x16_bf16 a[64:79], v[56:59], v[44:47], a[64:79]
	ds_read_b128 v[128:131], v83 offset:0x8800
	v_mfma_f32_32x32x16_bf16 a[80:95], v[56:59], v[48:51], a[80:95]
	global_load_dwordx4 v[20:23], v147, s[16:17]
	s_waitcnt lgkmcnt(3)
	v_mfma_f32_32x32x16_bf16 a[96:111], v[60:63], v[44:47], a[96:111]
	ds_read_b128 v[86:89], v81 offset:0x8000
	v_mfma_f32_32x32x16_bf16 a[112:127], v[60:63], v[48:51], a[112:127]
	global_load_dwordx4 v[24:27], v147, s[18:19]
	s_waitcnt vmcnt(11)
	ds_write_b128 v84, v[106:109] offset:0
	s_waitcnt lgkmcnt(4)
	v_mfma_f32_32x32x16_bf16 a[16:31], v[64:67], v[44:47], a[16:31]
	ds_read_b128 v[90:93], v81 offset:0x8800
	s_waitcnt vmcnt(10)
	ds_write_b128 v84, v[110:113] offset:0x1000
	v_mfma_f32_32x32x16_bf16 a[0:15], v[64:67], v[48:51], a[0:15]
	ds_read_b128 v[94:97], v81 offset:0x9000
	s_waitcnt vmcnt(9)
	ds_write_b128 v84, v[114:117] offset:0x2000
	s_waitcnt lgkmcnt(5)
	v_mfma_f32_32x32x16_bf16 a[32:47], v[86:89], v[40:43], a[32:47]
	ds_read_b128 v[132:135], v81 offset:0x9800
	s_waitcnt vmcnt(8)
	ds_write_b128 v84, v[118:121] offset:0x3000
	v_mfma_f32_32x32x16_bf16 a[48:63], v[86:89], v[128:131], a[48:63]
	s_waitcnt vmcnt(7)
	ds_write_b128 v84, v[122:125] offset:0x4000
	s_waitcnt lgkmcnt(6)
	v_mfma_f32_32x32x16_bf16 a[64:79], v[90:93], v[40:43], a[64:79]
	s_waitcnt vmcnt(6)
	ds_write_b128 v84, v[140:143] offset:0x5000
	v_mfma_f32_32x32x16_bf16 a[80:95], v[90:93], v[128:131], a[80:95]
	s_waitcnt lgkmcnt(0)
	s_mov_b32 s4, s5
	s_add_i32 s5, s4, 64
	s_min_u32 s6, s5, 0x3e0
	s_lshl_b32 s78, s6, 1
.Lrs4_top:
	s_barrier
	ds_read_b128 v[48:51], v82 offset:0
	ds_read_b128 v[44:47], v82 offset:0x800
	ds_read_b128 v[64:67], v80 offset:0
	v_mfma_f32_32x32x16_bf16 a[96:111], v[94:97], v[40:43], a[96:111]
	ds_read_b128 v[60:63], v80 offset:0x800
	v_mfma_f32_32x32x16_bf16 a[112:127], v[94:97], v[128:131], a[112:127]
	ds_read_b128 v[56:59], v80 offset:0x1000
	v_add_u32_e32 v146, s78, v144
	v_add_u32_e32 v147, s78, v145
	global_load_dwordx4 v[106:109], v146, s[8:9]
	v_mfma_f32_32x32x16_bf16 a[16:31], v[132:135], v[40:43], a[16:31]
	ds_read_b128 v[52:55], v80 offset:0x1800
	global_load_dwordx4 v[110:113], v146, s[10:11]
	v_mfma_f32_32x32x16_bf16 a[0:15], v[132:135], v[128:131], a[0:15]
	global_load_dwordx4 v[114:117], v146, s[12:13]
	s_waitcnt lgkmcnt(3)
	v_mfma_f32_32x32x16_bf16 a[32:47], v[64:67], v[48:51], a[32:47]
	ds_read_b128 v[40:43], v83 offset:0
	v_mfma_f32_32x32x16_bf16 a[48:63], v[64:67], v[44:47], a[48:63]
	global_load_dwordx4 v[118:121], v146, s[14:15]
	s_waitcnt lgkmcnt(3)
	v_mfma_f32_32x32x16_bf16 a[64:79], v[60:63], v[48:51], a[64:79]
	ds_read_b128 v[86:89], v83 offset:0x800
	v_mfma_f32_32x32x16_bf16 a[80:95], v[60:63], v[44:47], a[80:95]
	global_load_dwordx4 v[122:125], v147, s[16:17]
	s_waitcnt lgkmcnt(3)
	v_mfma_f32_32x32x16_bf16 a[96:111], v[56:59], v[48:51], a[96:111]
	ds_read_b128 v[90:93], v81 offset:0
	v_mfma_f32_32x32x16_bf16 a[112:127], v[56:59], v[44:47], a[112:127]
	global_load_dwordx4 v[140:143], v147, s[18:19]
	s_waitcnt vmcnt(11)
	ds_write_b128 v84, v[4:7] offset:0x8000
	s_waitcnt lgkmcnt(4)
	v_mfma_f32_32x32x16_bf16 a[16:31], v[52:55], v[48:51], a[16:31]
	ds_read_b128 v[94:97], v81 offset:0x800
	s_min_u32 s4, s4, 0x380
	s_lshl_b32 s78, s4, 1
	s_waitcnt vmcnt(10)
	ds_write_b128 v84, v[8:11] offset:0x9000
	v_mfma_f32_32x32x16_bf16 a[0:15], v[52:55], v[44:47], a[0:15]
	ds_read_b128 v[98:101], v81 offset:0x1000
	s_add_i32 s6, s78, 0xc0
	s_mov_b32 s7, s79
	s_waitcnt vmcnt(9)
	ds_write_b128 v84, v[12:15] offset:0xa000
	s_waitcnt lgkmcnt(5)
	v_mfma_f32_32x32x16_bf16 a[32:47], v[90:93], v[40:43], a[32:47]
	ds_read_b128 v[102:105], v81 offset:0x1800
	s_add_i32 s3, s3, 2
	s_cmp_lt_u32 s3, 28
	s_waitcnt vmcnt(8)
	ds_write_b128 v84, v[16:19] offset:0xb000
	v_mfma_f32_32x32x16_bf16 a[48:63], v[90:93], v[86:89], a[48:63]
	s_waitcnt vmcnt(7)
	ds_write_b128 v84, v[20:23] offset:0xc000
	s_waitcnt lgkmcnt(6)
	v_mfma_f32_32x32x16_bf16 a[64:79], v[94:97], v[40:43], a[64:79]
	s_waitcnt vmcnt(6)
	ds_write_b128 v84, v[24:27] offset:0xd000
	v_mfma_f32_32x32x16_bf16 a[80:95], v[94:97], v[86:89], a[80:95]
	s_waitcnt lgkmcnt(0)
	s_barrier
	ds_read_b128 v[44:47], v82 offset:0x8000
	ds_read_b128 v[48:51], v82 offset:0x8800
	ds_read_b128 v[52:55], v80 offset:0x8000
	v_mfma_f32_32x32x16_bf16 a[96:111], v[98:101], v[40:43], a[96:111]
	ds_read_b128 v[56:59], v80 offset:0x8800
	v_mfma_f32_32x32x16_bf16 a[112:127], v[98:101], v[86:89], a[112:127]
	ds_read_b128 v[60:63], v80 offset:0x9000
	v_add_u32_e32 v146, s6, v144
	v_add_u32_e32 v147, s6, v145
	global_load_dwordx4 v[4:7], v146, s[8:9]
	v_mfma_f32_32x32x16_bf16 a[16:31], v[102:105], v[40:43], a[16:31]
	ds_read_b128 v[64:67], v80 offset:0x9800
	global_load_dwordx4 v[8:11], v146, s[10:11]
	v_mfma_f32_32x32x16_bf16 a[0:15], v[102:105], v[86:89], a[0:15]
	global_load_dwordx4 v[12:15], v146, s[12:13]
	s_waitcnt lgkmcnt(3)
	v_mfma_f32_32x32x16_bf16 a[32:47], v[52:55], v[44:47], a[32:47]
	ds_read_b128 v[40:43], v83 offset:0x8000
	v_mfma_f32_32x32x16_bf16 a[48:63], v[52:55], v[48:51], a[48:63]
	global_load_dwordx4 v[16:19], v146, s[14:15]
	s_waitcnt lgkmcnt(3)
	v_mfma_f32_32x32x16_bf16 a[64:79], v[56:59], v[44:47], a[64:79]
	ds_read_b128 v[128:131], v83 offset:0x8800
	v_mfma_f32_32x32x16_bf16 a[80:95], v[56:59], v[48:51], a[80:95]
	global_load_dwordx4 v[20:23], v147, s[16:17]
	s_waitcnt lgkmcnt(3)
	v_mfma_f32_32x32x16_bf16 a[96:111], v[60:63], v[44:47], a[96:111]
	ds_read_b128 v[86:89], v81 offset:0x8000
	v_mfma_f32_32x32x16_bf16 a[112:127], v[60:63], v[48:51], a[112:127]
	global_load_dwordx4 v[24:27], v147, s[18:19]
	s_waitcnt vmcnt(11)
	ds_write_b128 v84, v[106:109] offset:0
	s_waitcnt lgkmcnt(4)
	v_mfma_f32_32x32x16_bf16 a[16:31], v[64:67], v[44:47], a[16:31]
	ds_read_b128 v[90:93], v81 offset:0x8800
	s_waitcnt vmcnt(10)
	ds_write_b128 v84, v[110:113] offset:0x1000
	v_mfma_f32_32x32x16_bf16 a[0:15], v[64:67], v[48:51], a[0:15]
	ds_read_b128 v[94:97], v81 offset:0x9000
	s_waitcnt vmcnt(9)
	ds_write_b128 v84, v[114:117] offset:0x2000
	s_waitcnt lgkmcnt(5)
	v_mfma_f32_32x32x16_bf16 a[32:47], v[86:89], v[40:43], a[32:47]
	ds_read_b128 v[132:135], v81 offset:0x9800
	s_waitcnt vmcnt(8)
	ds_write_b128 v84, v[118:121] offset:0x3000
	v_mfma_f32_32x32x16_bf16 a[48:63], v[86:89], v[128:131], a[48:63]
	s_waitcnt vmcnt(7)
	ds_write_b128 v84, v[122:125] offset:0x4000
	s_waitcnt lgkmcnt(6)
	v_mfma_f32_32x32x16_bf16 a[64:79], v[90:93], v[40:43], a[64:79]
	s_waitcnt vmcnt(6)
	ds_write_b128 v84, v[140:143] offset:0x5000
	v_mfma_f32_32x32x16_bf16 a[80:95], v[90:93], v[128:131], a[80:95]
	s_waitcnt lgkmcnt(0)
	s_cbranch_scc0 .Lrs4_last
	s_mov_b32 s4, s5
	s_add_i32 s5, s4, 64
	s_min_u32 s6, s5, 0x3e0
	s_lshl_b32 s78, s6, 1
	s_branch .Lrs4_top
.Lrs4_last:
	s_barrier
	s_mov_b32 s4, s5
	s_add_i32 s5, s4, 64
	s_min_u32 s6, s5, 0x3e0
	s_lshl_b32 s78, s6, 1
	ds_read_b128 v[48:51], v82 offset:0
	ds_read_b128 v[44:47], v82 offset:0x800
	ds_read_b128 v[64:67], v80 offset:0
	v_mfma_f32_32x32x16_bf16 a[96:111], v[94:97], v[40:43], a[96:111]
	ds_read_b128 v[60:63], v80 offset:0x800
	v_mfma_f32_32x32x16_bf16 a[112:127], v[94:97], v[128:131], a[112:127]
	ds_read_b128 v[56:59], v80 offset:0x1000
	v_mfma_f32_32x32x16_bf16 a[16:31], v[132:135], v[40:43], a[16:31]
	ds_read_b128 v[52:55], v80 offset:0x1800
	v_mfma_f32_32x32x16_bf16 a[0:15], v[132:135], v[128:131], a[0:15]
	s_waitcnt lgkmcnt(3)
	v_mfma_f32_32x32x16_bf16 a[32:47], v[64:67], v[48:51], a[32:47]
	ds_read_b128 v[40:43], v83 offset:0
	v_mfma_f32_32x32x16_bf16 a[48:63], v[64:67], v[44:47], a[48:63]
	s_waitcnt lgkmcnt(3)
	v_mfma_f32_32x32x16_bf16 a[64:79], v[60:63], v[48:51], a[64:79]
	ds_read_b128 v[86:89], v83 offset:0x800
	v_mfma_f32_32x32x16_bf16 a[80:95], v[60:63], v[44:47], a[80:95]
	s_waitcnt lgkmcnt(3)
	v_mfma_f32_32x32x16_bf16 a[96:111], v[56:59], v[48:51], a[96:111]
	ds_read_b128 v[90:93], v81 offset:0
	v_mfma_f32_32x32x16_bf16 a[112:127], v[56:59], v[44:47], a[112:127]
	s_waitcnt vmcnt(5)
	ds_write_b128 v84, v[4:7] offset:0x8000
	s_waitcnt lgkmcnt(4)
	v_mfma_f32_32x32x16_bf16 a[16:31], v[52:55], v[48:51], a[16:31]
	ds_read_b128 v[94:97], v81 offset:0x800
	s_min_u32 s4, s4, 0x380
	s_lshl_b32 s78, s4, 1
	s_waitcnt vmcnt(4)
	ds_write_b128 v84, v[8:11] offset:0x9000
	v_mfma_f32_32x32x16_bf16 a[0:15], v[52:55], v[44:47], a[0:15]
	ds_read_b128 v[98:101], v81 offset:0x1000
	s_add_i32 s6, s78, 0xc0
	s_mov_b32 s7, s79
	s_waitcnt vmcnt(3)
	ds_write_b128 v84, v[12:15] offset:0xa000
	s_waitcnt lgkmcnt(5)
	v_mfma_f32_32x32x16_bf16 a[32:47], v[90:93], v[40:43], a[32:47]
	ds_read_b128 v[102:105], v81 offset:0x1800
	s_add_i32 s3, s3, 2
	s_cmp_lt_u32 s3, 30
	s_waitcnt vmcnt(2)
	ds_write_b128 v84, v[16:19] offset:0xb000
	v_mfma_f32_32x32x16_bf16 a[48:63], v[90:93], v[86:89], a[48:63]
	s_waitcnt vmcnt(1)
	ds_write_b128 v84, v[20:23] offset:0xc000
	s_waitcnt lgkmcnt(6)
	v_mfma_f32_32x32x16_bf16 a[64:79], v[94:97], v[40:43], a[64:79]
	s_waitcnt vmcnt(0)
	ds_write_b128 v84, v[24:27] offset:0xd000
	v_mfma_f32_32x32x16_bf16 a[80:95], v[94:97], v[86:89], a[80:95]
	s_waitcnt lgkmcnt(0)
	s_barrier
	ds_read_b128 v[44:47], v82 offset:0x8000
	ds_read_b128 v[48:51], v82 offset:0x8800
	ds_read_b128 v[52:55], v80 offset:0x8000
	v_mfma_f32_32x32x16_bf16 a[96:111], v[98:101], v[40:43], a[96:111]
	ds_read_b128 v[56:59], v80 offset:0x8800
	v_mfma_f32_32x32x16_bf16 a[112:127], v[98:101], v[86:89], a[112:127]
	ds_read_b128 v[60:63], v80 offset:0x9000
	v_mfma_f32_32x32x16_bf16 a[16:31], v[102:105], v[40:43], a[16:31]
	ds_read_b128 v[64:67], v80 offset:0x9800
	v_mfma_f32_32x32x16_bf16 a[0:15], v[102:105], v[86:89], a[0:15]
	s_waitcnt lgkmcnt(3)
	v_mfma_f32_32x32x16_bf16 a[32:47], v[52:55], v[44:47], a[32:47]
	ds_read_b128 v[40:43], v83 offset:0x8000
	v_mfma_f32_32x32x16_bf16 a[48:63], v[52:55], v[48:51], a[48:63]
	s_waitcnt lgkmcnt(3)
	v_mfma_f32_32x32x16_bf16 a[64:79], v[56:59], v[44:47], a[64:79]
	ds_read_b128 v[128:131], v83 offset:0x8800
	v_mfma_f32_32x32x16_bf16 a[80:95], v[56:59], v[48:51], a[80:95]
	s_waitcnt lgkmcnt(3)
	v_mfma_f32_32x32x16_bf16 a[96:111], v[60:63], v[44:47], a[96:111]
	ds_read_b128 v[86:89], v81 offset:0x8000
	v_mfma_f32_32x32x16_bf16 a[112:127], v[60:63], v[48:51], a[112:127]
	s_waitcnt lgkmcnt(3)
	v_mfma_f32_32x32x16_bf16 a[16:31], v[64:67], v[44:47], a[16:31]
	ds_read_b128 v[90:93], v81 offset:0x8800
	v_mfma_f32_32x32x16_bf16 a[0:15], v[64:67], v[48:51], a[0:15]
	ds_read_b128 v[94:97], v81 offset:0x9000
	s_waitcnt lgkmcnt(2)
	v_mfma_f32_32x32x16_bf16 a[32:47], v[86:89], v[40:43], a[32:47]
	ds_read_b128 v[132:135], v81 offset:0x9800
	v_mfma_f32_32x32x16_bf16 a[48:63], v[86:89], v[128:131], a[48:63]
	s_waitcnt lgkmcnt(2)
	v_mfma_f32_32x32x16_bf16 a[64:79], v[90:93], v[40:43], a[64:79]
	v_mfma_f32_32x32x16_bf16 a[80:95], v[90:93], v[128:131], a[80:95]
	s_waitcnt lgkmcnt(0)
	s_barrier
	v_mfma_f32_32x32x16_bf16 a[96:111], v[94:97], v[40:43], a[96:111]
	v_mfma_f32_32x32x16_bf16 a[112:127], v[94:97], v[128:131], a[112:127]
	s_nop 7
	s_nop 3
	s_branch .LBB0_222

.LBB0_773:
	v_readfirstlane_b32 s8, v64
	v_readfirstlane_b32 s9, v65
	v_readfirstlane_b32 s10, v68
	v_readfirstlane_b32 s11, v69
	v_readfirstlane_b32 s12, v70
	v_readfirstlane_b32 s13, v71
	v_readfirstlane_b32 s14, v72
	v_readfirstlane_b32 s15, v73
	v_readfirstlane_b32 s16, v66
	v_readfirstlane_b32 s17, v67
	v_readfirstlane_b32 s18, v74
	v_readfirstlane_b32 s19, v75
	v_subrev_u32_e32 v140, s8, v64
	v_subrev_u32_e32 v141, s16, v66
	s_nop 4
	s_add_i32 s4, s3, 64
	s_min_u32 s5, s4, 0x3e0
	s_lshl_b32 s78, s5, 1
	ds_read_b128 v[44:47], v78 offset:0
	ds_read_b128 v[40:43], v78 offset:0x800
	ds_read_b128 v[60:63], v76 offset:0
	ds_read_b128 v[56:59], v76 offset:0x800
	ds_read_b128 v[52:55], v76 offset:0x1000
	v_add_u32_e32 v142, s78, v140
	v_add_u32_e32 v143, s78, v141
	global_load_dwordx4 v[106:109], v142, s[8:9]
	ds_read_b128 v[48:51], v76 offset:0x1800
	global_load_dwordx4 v[110:113], v142, s[10:11]
	global_load_dwordx4 v[114:117], v142, s[12:13]
	s_waitcnt lgkmcnt(3)
	v_mfma_f32_32x32x16_bf16 a[112:127], v[60:63], v[44:47], 0
	ds_read_b128 v[82:85], v79 offset:0
	v_mfma_f32_32x32x16_bf16 a[96:111], v[60:63], v[40:43], 0
	global_load_dwordx4 v[118:121], v142, s[14:15]
	s_waitcnt lgkmcnt(3)
	v_mfma_f32_32x32x16_bf16 a[80:95], v[56:59], v[44:47], 0
	ds_read_b128 v[86:89], v79 offset:0x800
	v_mfma_f32_32x32x16_bf16 a[64:79], v[56:59], v[40:43], 0
	global_load_dwordx4 v[122:125], v143, s[16:17]
	s_waitcnt lgkmcnt(3)
	v_mfma_f32_32x32x16_bf16 a[48:63], v[52:55], v[44:47], 0
	ds_read_b128 v[90:93], v77 offset:0
	v_mfma_f32_32x32x16_bf16 a[16:31], v[52:55], v[40:43], 0
	global_load_dwordx4 v[126:129], v143, s[18:19]
	s_waitcnt vmcnt(11)
	ds_write_b128 v80, v[4:7] offset:0x8000
	s_waitcnt lgkmcnt(4)
	v_mfma_f32_32x32x16_bf16 a[0:15], v[48:51], v[44:47], 0
	ds_read_b128 v[94:97], v77 offset:0x800
	s_min_u32 s3, s3, 0x380
	s_lshl_b32 s78, s3, 1
	s_waitcnt vmcnt(10)
	ds_write_b128 v80, v[8:11] offset:0x9000
	v_mfma_f32_32x32x16_bf16 a[128:143], v[48:51], v[40:43], 0
	ds_read_b128 v[98:101], v77 offset:0x1000
	s_add_i32 s6, s78, 0xc0
	s_mov_b32 s7, s79
	s_waitcnt vmcnt(9)
	ds_write_b128 v80, v[12:15] offset:0xa000
	s_waitcnt lgkmcnt(5)
	v_mfma_f32_32x32x16_bf16 a[112:127], v[90:93], v[82:85], a[112:127]
	ds_read_b128 v[102:105], v77 offset:0x1800
	s_add_i32 s2, s2, 2
	s_cmp_gt_u32 s2, 29
	s_waitcnt vmcnt(8)
	ds_write_b128 v80, v[16:19] offset:0xb000
	v_mfma_f32_32x32x16_bf16 a[96:111], v[90:93], v[86:89], a[96:111]
	s_waitcnt vmcnt(7)
	ds_write_b128 v80, v[20:23] offset:0xc000
	s_waitcnt lgkmcnt(6)
	v_mfma_f32_32x32x16_bf16 a[80:95], v[94:97], v[82:85], a[80:95]
	s_waitcnt vmcnt(6)
	ds_write_b128 v80, v[24:27] offset:0xd000
	v_mfma_f32_32x32x16_bf16 a[64:79], v[94:97], v[86:89], a[64:79]
	s_waitcnt lgkmcnt(0)
	s_barrier
	ds_read_b128 v[40:43], v78 offset:0x8000
	ds_read_b128 v[44:47], v78 offset:0x8800
	ds_read_b128 v[48:51], v76 offset:0x8000
	v_mfma_f32_32x32x16_bf16 a[48:63], v[98:101], v[82:85], a[48:63]
	ds_read_b128 v[52:55], v76 offset:0x8800
	v_mfma_f32_32x32x16_bf16 a[16:31], v[98:101], v[86:89], a[16:31]
	ds_read_b128 v[56:59], v76 offset:0x9000
	v_add_u32_e32 v142, s6, v140
	v_add_u32_e32 v143, s6, v141
	global_load_dwordx4 v[4:7], v142, s[8:9]
	v_mfma_f32_32x32x16_bf16 a[0:15], v[102:105], v[82:85], a[0:15]
	ds_read_b128 v[60:63], v76 offset:0x9800
	global_load_dwordx4 v[8:11], v142, s[10:11]
	v_mfma_f32_32x32x16_bf16 a[128:143], v[102:105], v[86:89], a[128:143]
	global_load_dwordx4 v[12:15], v142, s[12:13]
	s_waitcnt lgkmcnt(3)
	v_mfma_f32_32x32x16_bf16 a[112:127], v[48:51], v[40:43], a[112:127]
	ds_read_b128 v[202:205], v79 offset:0x8000
	v_mfma_f32_32x32x16_bf16 a[96:111], v[48:51], v[44:47], a[96:111]
	global_load_dwordx4 v[16:19], v142, s[14:15]
	s_waitcnt lgkmcnt(3)
	v_mfma_f32_32x32x16_bf16 a[80:95], v[52:55], v[40:43], a[80:95]
	ds_read_b128 v[194:197], v79 offset:0x8800
	v_mfma_f32_32x32x16_bf16 a[64:79], v[52:55], v[44:47], a[64:79]
	global_load_dwordx4 v[20:23], v143, s[16:17]
	s_waitcnt lgkmcnt(3)
	v_mfma_f32_32x32x16_bf16 a[48:63], v[56:59], v[40:43], a[48:63]
	ds_read_b128 v[82:85], v77 offset:0x8000
	v_mfma_f32_32x32x16_bf16 a[16:31], v[56:59], v[44:47], a[16:31]
	global_load_dwordx4 v[24:27], v143, s[18:19]
	s_waitcnt vmcnt(11)
	ds_write_b128 v80, v[106:109] offset:0
	s_waitcnt lgkmcnt(4)
	v_mfma_f32_32x32x16_bf16 a[0:15], v[60:63], v[40:43], a[0:15]
	ds_read_b128 v[86:89], v77 offset:0x8800
	s_waitcnt vmcnt(10)
	ds_write_b128 v80, v[110:113] offset:0x1000
	v_mfma_f32_32x32x16_bf16 a[128:143], v[60:63], v[44:47], a[128:143]
	ds_read_b128 v[90:93], v77 offset:0x9000
	s_waitcnt vmcnt(9)
	ds_write_b128 v80, v[114:117] offset:0x2000
	s_waitcnt lgkmcnt(5)
	v_mfma_f32_32x32x16_bf16 a[112:127], v[82:85], v[202:205], a[112:127]
	ds_read_b128 v[198:201], v77 offset:0x9800
	s_waitcnt vmcnt(8)
	ds_write_b128 v80, v[118:121] offset:0x3000
	v_mfma_f32_32x32x16_bf16 a[96:111], v[82:85], v[194:197], a[96:111]
	s_waitcnt vmcnt(7)
	ds_write_b128 v80, v[122:125] offset:0x4000
	s_waitcnt lgkmcnt(6)
	v_mfma_f32_32x32x16_bf16 a[80:95], v[86:89], v[202:205], a[80:95]
	s_waitcnt vmcnt(6)
	ds_write_b128 v80, v[126:129] offset:0x5000
	v_mfma_f32_32x32x16_bf16 a[64:79], v[86:89], v[194:197], a[64:79]
	s_waitcnt lgkmcnt(0)
	s_mov_b32 s3, s4
	s_add_i32 s4, s3, 64
	s_min_u32 s5, s4, 0x3e0
	s_lshl_b32 s78, s5, 1
.Lrs5_top:
	s_barrier
	ds_read_b128 v[44:47], v78 offset:0
	ds_read_b128 v[40:43], v78 offset:0x800
	ds_read_b128 v[60:63], v76 offset:0
	v_mfma_f32_32x32x16_bf16 a[48:63], v[90:93], v[202:205], a[48:63]
	ds_read_b128 v[56:59], v76 offset:0x800
	v_mfma_f32_32x32x16_bf16 a[16:31], v[90:93], v[194:197], a[16:31]
	ds_read_b128 v[52:55], v76 offset:0x1000
	v_add_u32_e32 v142, s78, v140
	v_add_u32_e32 v143, s78, v141
	global_load_dwordx4 v[106:109], v142, s[8:9]
	v_mfma_f32_32x32x16_bf16 a[0:15], v[198:201], v[202:205], a[0:15]
	ds_read_b128 v[48:51], v76 offset:0x1800
	global_load_dwordx4 v[110:113], v142, s[10:11]
	v_mfma_f32_32x32x16_bf16 a[128:143], v[198:201], v[194:197], a[128:143]
	global_load_dwordx4 v[114:117], v142, s[12:13]
	s_waitcnt lgkmcnt(3)
	v_mfma_f32_32x32x16_bf16 a[112:127], v[60:63], v[44:47], a[112:127]
	ds_read_b128 v[82:85], v79 offset:0
	v_mfma_f32_32x32x16_bf16 a[96:111], v[60:63], v[40:43], a[96:111]
	global_load_dwordx4 v[118:121], v142, s[14:15]
	s_waitcnt lgkmcnt(3)
	v_mfma_f32_32x32x16_bf16 a[80:95], v[56:59], v[44:47], a[80:95]
	ds_read_b128 v[86:89], v79 offset:0x800
	v_mfma_f32_32x32x16_bf16 a[64:79], v[56:59], v[40:43], a[64:79]
	global_load_dwordx4 v[122:125], v143, s[16:17]
	s_waitcnt lgkmcnt(3)
	v_mfma_f32_32x32x16_bf16 a[48:63], v[52:55], v[44:47], a[48:63]
	ds_read_b128 v[90:93], v77 offset:0
	v_mfma_f32_32x32x16_bf16 a[16:31], v[52:55], v[40:43], a[16:31]
	global_load_dwordx4 v[126:129], v143, s[18:19]
	s_waitcnt vmcnt(11)
	ds_write_b128 v80, v[4:7] offset:0x8000
	s_waitcnt lgkmcnt(4)
	v_mfma_f32_32x32x16_bf16 a[0:15], v[48:51], v[44:47], a[0:15]
	ds_read_b128 v[94:97], v77 offset:0x800
	s_min_u32 s3, s3, 0x380
	s_lshl_b32 s78, s3, 1
	s_waitcnt vmcnt(10)
	ds_write_b128 v80, v[8:11] offset:0x9000
	v_mfma_f32_32x32x16_bf16 a[128:143], v[48:51], v[40:43], a[128:143]
	ds_read_b128 v[98:101], v77 offset:0x1000
	s_add_i32 s6, s78, 0xc0
	s_mov_b32 s7, s79
	s_waitcnt vmcnt(9)
	ds_write_b128 v80, v[12:15] offset:0xa000
	s_waitcnt lgkmcnt(5)
	v_mfma_f32_32x32x16_bf16 a[112:127], v[90:93], v[82:85], a[112:127]
	ds_read_b128 v[102:105], v77 offset:0x1800
	s_add_i32 s2, s2, 2
	s_cmp_gt_u32 s2, 27
	s_waitcnt vmcnt(8)
	ds_write_b128 v80, v[16:19] offset:0xb000
	v_mfma_f32_32x32x16_bf16 a[96:111], v[90:93], v[86:89], a[96:111]
	s_waitcnt vmcnt(7)
	ds_write_b128 v80, v[20:23] offset:0xc000
	s_waitcnt lgkmcnt(6)
	v_mfma_f32_32x32x16_bf16 a[80:95], v[94:97], v[82:85], a[80:95]
	s_waitcnt vmcnt(6)
	ds_write_b128 v80, v[24:27] offset:0xd000
	v_mfma_f32_32x32x16_bf16 a[64:79], v[94:97], v[86:89], a[64:79]
	s_waitcnt lgkmcnt(0)
	s_barrier
	ds_read_b128 v[40:43], v78 offset:0x8000
	ds_read_b128 v[44:47], v78 offset:0x8800
	ds_read_b128 v[48:51], v76 offset:0x8000
	v_mfma_f32_32x32x16_bf16 a[48:63], v[98:101], v[82:85], a[48:63]
	ds_read_b128 v[52:55], v76 offset:0x8800
	v_mfma_f32_32x32x16_bf16 a[16:31], v[98:101], v[86:89], a[16:31]
	ds_read_b128 v[56:59], v76 offset:0x9000
	v_add_u32_e32 v142, s6, v140
	v_add_u32_e32 v143, s6, v141
	global_load_dwordx4 v[4:7], v142, s[8:9]
	v_mfma_f32_32x32x16_bf16 a[0:15], v[102:105], v[82:85], a[0:15]
	ds_read_b128 v[60:63], v76 offset:0x9800
	global_load_dwordx4 v[8:11], v142, s[10:11]
	v_mfma_f32_32x32x16_bf16 a[128:143], v[102:105], v[86:89], a[128:143]
	global_load_dwordx4 v[12:15], v142, s[12:13]
	s_waitcnt lgkmcnt(3)
	v_mfma_f32_32x32x16_bf16 a[112:127], v[48:51], v[40:43], a[112:127]
	ds_read_b128 v[202:205], v79 offset:0x8000
	v_mfma_f32_32x32x16_bf16 a[96:111], v[48:51], v[44:47], a[96:111]
	global_load_dwordx4 v[16:19], v142, s[14:15]
	s_waitcnt lgkmcnt(3)
	v_mfma_f32_32x32x16_bf16 a[80:95], v[52:55], v[40:43], a[80:95]
	ds_read_b128 v[194:197], v79 offset:0x8800
	v_mfma_f32_32x32x16_bf16 a[64:79], v[52:55], v[44:47], a[64:79]
	global_load_dwordx4 v[20:23], v143, s[16:17]
	s_waitcnt lgkmcnt(3)
	v_mfma_f32_32x32x16_bf16 a[48:63], v[56:59], v[40:43], a[48:63]
	ds_read_b128 v[82:85], v77 offset:0x8000
	v_mfma_f32_32x32x16_bf16 a[16:31], v[56:59], v[44:47], a[16:31]
	global_load_dwordx4 v[24:27], v143, s[18:19]
	s_waitcnt vmcnt(11)
	ds_write_b128 v80, v[106:109] offset:0
	s_waitcnt lgkmcnt(4)
	v_mfma_f32_32x32x16_bf16 a[0:15], v[60:63], v[40:43], a[0:15]
	ds_read_b128 v[86:89], v77 offset:0x8800
	s_waitcnt vmcnt(10)
	ds_write_b128 v80, v[110:113] offset:0x1000
	v_mfma_f32_32x32x16_bf16 a[128:143], v[60:63], v[44:47], a[128:143]
	ds_read_b128 v[90:93], v77 offset:0x9000
	s_waitcnt vmcnt(9)
	ds_write_b128 v80, v[114:117] offset:0x2000
	s_waitcnt lgkmcnt(5)
	v_mfma_f32_32x32x16_bf16 a[112:127], v[82:85], v[202:205], a[112:127]
	ds_read_b128 v[198:201], v77 offset:0x9800
	s_waitcnt vmcnt(8)
	ds_write_b128 v80, v[118:121] offset:0x3000
	v_mfma_f32_32x32x16_bf16 a[96:111], v[82:85], v[194:197], a[96:111]
	s_waitcnt vmcnt(7)
	ds_write_b128 v80, v[122:125] offset:0x4000
	s_waitcnt lgkmcnt(6)
	v_mfma_f32_32x32x16_bf16 a[80:95], v[86:89], v[202:205], a[80:95]
	s_waitcnt vmcnt(6)
	ds_write_b128 v80, v[126:129] offset:0x5000
	v_mfma_f32_32x32x16_bf16 a[64:79], v[86:89], v[194:197], a[64:79]
	s_waitcnt lgkmcnt(0)
	s_cbranch_scc1 .Lrs5_last
	s_mov_b32 s3, s4
	s_add_i32 s4, s3, 64
	s_min_u32 s5, s4, 0x3e0
	s_lshl_b32 s78, s5, 1
	s_branch .Lrs5_top
.Lrs5_last:
	s_barrier
	s_mov_b32 s3, s4
	s_add_i32 s4, s3, 64
	s_min_u32 s5, s4, 0x3e0
	s_lshl_b32 s78, s5, 1
	ds_read_b128 v[44:47], v78 offset:0
	ds_read_b128 v[40:43], v78 offset:0x800
	ds_read_b128 v[60:63], v76 offset:0
	v_mfma_f32_32x32x16_bf16 a[48:63], v[90:93], v[202:205], a[48:63]
	ds_read_b128 v[56:59], v76 offset:0x800
	v_mfma_f32_32x32x16_bf16 a[16:31], v[90:93], v[194:197], a[16:31]
	ds_read_b128 v[52:55], v76 offset:0x1000
	v_mfma_f32_32x32x16_bf16 a[0:15], v[198:201], v[202:205], a[0:15]
	ds_read_b128 v[48:51], v76 offset:0x1800
	v_mfma_f32_32x32x16_bf16 a[128:143], v[198:201], v[194:197], a[128:143]
	s_waitcnt lgkmcnt(3)
	v_mfma_f32_32x32x16_bf16 a[112:127], v[60:63], v[44:47], a[112:127]
	ds_read_b128 v[82:85], v79 offset:0
	v_mfma_f32_32x32x16_bf16 a[96:111], v[60:63], v[40:43], a[96:111]
	s_waitcnt lgkmcnt(3)
	v_mfma_f32_32x32x16_bf16 a[80:95], v[56:59], v[44:47], a[80:95]
	ds_read_b128 v[86:89], v79 offset:0x800
	v_mfma_f32_32x32x16_bf16 a[64:79], v[56:59], v[40:43], a[64:79]
	s_waitcnt lgkmcnt(3)
	v_mfma_f32_32x32x16_bf16 a[48:63], v[52:55], v[44:47], a[48:63]
	ds_read_b128 v[90:93], v77 offset:0
	v_mfma_f32_32x32x16_bf16 a[16:31], v[52:55], v[40:43], a[16:31]
	s_waitcnt vmcnt(5)
	ds_write_b128 v80, v[4:7] offset:0x8000
	s_waitcnt lgkmcnt(4)
	v_mfma_f32_32x32x16_bf16 a[0:15], v[48:51], v[44:47], a[0:15]
	ds_read_b128 v[94:97], v77 offset:0x800
	s_min_u32 s3, s3, 0x380
	s_lshl_b32 s78, s3, 1
	s_waitcnt vmcnt(4)
	ds_write_b128 v80, v[8:11] offset:0x9000
	v_mfma_f32_32x32x16_bf16 a[128:143], v[48:51], v[40:43], a[128:143]
	ds_read_b128 v[98:101], v77 offset:0x1000
	s_add_i32 s6, s78, 0xc0
	s_mov_b32 s7, s79
	s_waitcnt vmcnt(3)
	ds_write_b128 v80, v[12:15] offset:0xa000
	s_waitcnt lgkmcnt(5)
	v_mfma_f32_32x32x16_bf16 a[112:127], v[90:93], v[82:85], a[112:127]
	ds_read_b128 v[102:105], v77 offset:0x1800
	s_add_i32 s2, s2, 2
	s_cmp_gt_u32 s2, 29
	s_waitcnt vmcnt(2)
	ds_write_b128 v80, v[16:19] offset:0xb000
	v_mfma_f32_32x32x16_bf16 a[96:111], v[90:93], v[86:89], a[96:111]
	s_waitcnt vmcnt(1)
	ds_write_b128 v80, v[20:23] offset:0xc000
	s_waitcnt lgkmcnt(6)
	v_mfma_f32_32x32x16_bf16 a[80:95], v[94:97], v[82:85], a[80:95]
	s_waitcnt vmcnt(0)
	ds_write_b128 v80, v[24:27] offset:0xd000
	v_mfma_f32_32x32x16_bf16 a[64:79], v[94:97], v[86:89], a[64:79]
	s_waitcnt lgkmcnt(0)
	s_barrier
	ds_read_b128 v[40:43], v78 offset:0x8000
	ds_read_b128 v[44:47], v78 offset:0x8800
	ds_read_b128 v[48:51], v76 offset:0x8000
	v_mfma_f32_32x32x16_bf16 a[48:63], v[98:101], v[82:85], a[48:63]
	ds_read_b128 v[52:55], v76 offset:0x8800
	v_mfma_f32_32x32x16_bf16 a[16:31], v[98:101], v[86:89], a[16:31]
	ds_read_b128 v[56:59], v76 offset:0x9000
	v_mfma_f32_32x32x16_bf16 a[0:15], v[102:105], v[82:85], a[0:15]
	ds_read_b128 v[60:63], v76 offset:0x9800
	v_mfma_f32_32x32x16_bf16 a[128:143], v[102:105], v[86:89], a[128:143]
	s_waitcnt lgkmcnt(3)
	v_mfma_f32_32x32x16_bf16 a[112:127], v[48:51], v[40:43], a[112:127]
	ds_read_b128 v[202:205], v79 offset:0x8000
	v_mfma_f32_32x32x16_bf16 a[96:111], v[48:51], v[44:47], a[96:111]
	s_waitcnt lgkmcnt(3)
	v_mfma_f32_32x32x16_bf16 a[80:95], v[52:55], v[40:43], a[80:95]
	ds_read_b128 v[194:197], v79 offset:0x8800
	v_mfma_f32_32x32x16_bf16 a[64:79], v[52:55], v[44:47], a[64:79]
	s_waitcnt lgkmcnt(3)
	v_mfma_f32_32x32x16_bf16 a[48:63], v[56:59], v[40:43], a[48:63]
	ds_read_b128 v[82:85], v77 offset:0x8000
	v_mfma_f32_32x32x16_bf16 a[16:31], v[56:59], v[44:47], a[16:31]
	s_waitcnt lgkmcnt(3)
	v_mfma_f32_32x32x16_bf16 a[0:15], v[60:63], v[40:43], a[0:15]
	ds_read_b128 v[86:89], v77 offset:0x8800
	v_mfma_f32_32x32x16_bf16 a[128:143], v[60:63], v[44:47], a[128:143]
	ds_read_b128 v[90:93], v77 offset:0x9000
	s_waitcnt lgkmcnt(2)
	v_mfma_f32_32x32x16_bf16 a[112:127], v[82:85], v[202:205], a[112:127]
	ds_read_b128 v[198:201], v77 offset:0x9800
	v_mfma_f32_32x32x16_bf16 a[96:111], v[82:85], v[194:197], a[96:111]
	s_waitcnt lgkmcnt(2)
	v_mfma_f32_32x32x16_bf16 a[80:95], v[86:89], v[202:205], a[80:95]
	v_mfma_f32_32x32x16_bf16 a[64:79], v[86:89], v[194:197], a[64:79]
	s_waitcnt lgkmcnt(0)
	s_barrier
	v_mfma_f32_32x32x16_bf16 a[48:63], v[90:93], v[202:205], a[48:63]
	v_mfma_f32_32x32x16_bf16 a[16:31], v[90:93], v[194:197], a[16:31]
	s_nop 7
	s_nop 3
	s_branch .LBB0_777
